# all GEMM K-loops MFMA order variant m_all (A fragment held for 8 MFMAs, accumulate chains)
# baseline (speedup 1.0000x reference)
; #define PG8_STAGE(bufoff, gbase, voff) do { _Pragma("unroll") for (int _i = 0; _i < 2; ++_i) \
;         __builtin_amdgcn_global_load_lds((const unsigned*)((const char*)(gbase) + (voff)[_i]), (PG8_LAS unsigned*)(lds + (bufoff) + ldsw + _i * 8192), 16, 0, 0); } while (0)
; #define PG8_LDA(dst, b, h) do { _Pragma("unroll") for (int m = 0; m < 4; ++m) _Pragma("unroll") for (int k = 0; k < 2; ++k) dst[m][k] = *(const PG8_LAS bf16x8*)(lds + PG8_SA(b, h) + aoff + m * 2048 + k * 1024); } while (0)
; #define PG8_LDB(dst, b, h) do { _Pragma("unroll") for (int n = 0; n < 2; ++n) _Pragma("unroll") for (int k = 0; k < 2; ++k) dst[n][k] = *(const PG8_LAS bf16x8*)(lds + PG8_SB(b, h) + boff + n * 2048 + k * 1024); } while (0)
; #define PG8_WAIT_V(n) asm volatile("s_waitcnt vmcnt(" #n ")" ::: "memory")
; #define PG8_WAIT_L(n) asm volatile("s_waitcnt lgkmcnt(" #n ")" ::: "memory")
; #define PG8_BAR __builtin_amdgcn_s_barrier()
; #define PG8_SCHED __builtin_amdgcn_sched_barrier(0)
; template <class Epi, class Sched, bool ALIGN_EPI = false, bool SP2 = false>
; __device__ __forceinline__ void gemm_phase(PG8_LAS unsigned char* lds, const Gemm g, const Sched& S, const Epi& E) {
;     ...
;         const char* nA = has_next ? (const char*)g.A + (size_t)nxt.pm * tstep : cA; const char* nB = has_next ? (const char*)g.Bt + (size_t)nxt.pn * tstep : cB;
;         for (int t = 0; t < nt; t += 2) {
;             const bool last = (t == nt - 2);
;             const char* a1 = cA + (size_t)(t + 1) * kstep;
;             const char* a2 = last ? nA : cA + (size_t)(t + 2) * kstep; const char* b2 = last ? nB : cB + (size_t)(t + 2) * kstep;
;             const char* a3 = a2 + kstep; const char* b3 = b2 + kstep;
;             if (last && has_next) S.a_ready(nxt);
;             if constexpr (SP2) {
;             PG8_LDB(B0, 0, 0); PG8_LDB(B1, 0, 1); PG8_SCHED; PG8_LDA(At, 0, 0); PG8_STAGE(PG8_SA(1, 1), a1 + hstep, voffA);
;             PG8_WAIT_V(8); PG8_WAIT_L(0); PG8_BAR; PG8_MMA(0, 0, At, B0); PG8_MMA(0, 1, At, B1); PG8_BAR; PG8_SCHED;
;             PG8_LDA(At, 0, 1); PG8_STAGE(PG8_SB(0, 0), b2, voffB); PG8_STAGE(PG8_SB(0, 1), b2 + hstep, voffB); PG8_STAGE(PG8_SA(0, 0), a2, voffA);
;             PG8_WAIT_V(8); PG8_WAIT_L(0); PG8_BAR; PG8_MMA(1, 0, At, B0); PG8_MMA(1, 1, At, B1); PG8_BAR; PG8_SCHED;
.LBB11_228:
	ds_read_b128 v[152:155], v149
	ds_read_b128 v[156:159], v149 offset:1024
	ds_read_b128 v[160:163], v149 offset:2048
	ds_read_b128 v[164:167], v149 offset:3072
	ds_read_b128 v[168:171], v150
	ds_read_b128 v[172:175], v150 offset:1024
	ds_read_b128 v[176:179], v150 offset:2048
	ds_read_b128 v[180:183], v150 offset:3072
	s_add_u32 s30, s28, 0xfff80080
	s_addc_u32 s31, s29, -1
	s_cmp_eq_u32 s61, 28
	s_cselect_b32 s35, s21, s31
	s_cselect_b32 s34, s57, s30
	s_cselect_b32 s31, s19, s60
	s_cselect_b32 s30, s58, s59
	v_lshl_add_u64 v[144:145], s[28:29], 0, v[140:141]
	s_add_i32 m0, s27, 0xc000
	ds_read_b128 v[184:187], v151
	ds_read_b128 v[188:191], v151 offset:1024
	ds_read_b128 v[192:195], v151 offset:2048
	ds_read_b128 v[196:199], v151 offset:3072
	ds_read_b128 v[200:203], v151 offset:4096
	ds_read_b128 v[204:207], v151 offset:5120
	ds_read_b128 v[210:213], v151 offset:6144
	ds_read_b128 v[214:217], v151 offset:7168
	global_load_lds_dwordx4 v[144:145], off
	v_lshl_add_u64 v[144:145], s[28:29], 0, v[142:143]
	s_add_i32 m0, s27, 0xe000
	s_nop 0
	global_load_lds_dwordx4 v[144:145], off
	s_waitcnt vmcnt(8)
	s_waitcnt lgkmcnt(0)
	s_barrier
	s_setprio 1
	s_waitcnt lgkmcnt(0)
	v_mfma_f32_16x16x32_bf16 v[126:129], v[152:155], v[184:187], v[126:129]
	v_mfma_f32_16x16x32_bf16 v[126:129], v[156:159], v[188:191], v[126:129]
	v_mfma_f32_16x16x32_bf16 v[122:125], v[160:163], v[184:187], v[122:125]
	v_mfma_f32_16x16x32_bf16 v[122:125], v[164:167], v[188:191], v[122:125]
	v_mfma_f32_16x16x32_bf16 v[114:117], v[168:171], v[184:187], v[114:117]
	v_mfma_f32_16x16x32_bf16 v[114:117], v[172:175], v[188:191], v[114:117]
	v_mfma_f32_16x16x32_bf16 v[106:109], v[176:179], v[184:187], v[106:109]
	v_mfma_f32_16x16x32_bf16 v[106:109], v[180:183], v[188:191], v[106:109]
	v_mfma_f32_16x16x32_bf16 v[118:121], v[152:155], v[192:195], v[118:121]
	v_mfma_f32_16x16x32_bf16 v[118:121], v[156:159], v[196:199], v[118:121]
	v_mfma_f32_16x16x32_bf16 v[110:113], v[160:163], v[192:195], v[110:113]
	v_mfma_f32_16x16x32_bf16 v[110:113], v[164:167], v[196:199], v[110:113]
	v_mfma_f32_16x16x32_bf16 v[98:101], v[168:171], v[192:195], v[98:101]
	v_mfma_f32_16x16x32_bf16 v[98:101], v[172:175], v[196:199], v[98:101]
	v_mfma_f32_16x16x32_bf16 v[90:93], v[176:179], v[192:195], v[90:93]
	v_mfma_f32_16x16x32_bf16 v[90:93], v[180:183], v[196:199], v[90:93]
	s_setprio 0
	s_setprio 1
	v_mfma_f32_16x16x32_bf16 v[102:105], v[152:155], v[200:203], v[102:105]
	v_mfma_f32_16x16x32_bf16 v[102:105], v[156:159], v[204:207], v[102:105]
	v_mfma_f32_16x16x32_bf16 v[94:97], v[160:163], v[200:203], v[94:97]
	v_mfma_f32_16x16x32_bf16 v[94:97], v[164:167], v[204:207], v[94:97]
	v_mfma_f32_16x16x32_bf16 v[82:85], v[168:171], v[200:203], v[82:85]
	v_mfma_f32_16x16x32_bf16 v[82:85], v[172:175], v[204:207], v[82:85]
	v_mfma_f32_16x16x32_bf16 v[74:77], v[176:179], v[200:203], v[74:77]
	v_mfma_f32_16x16x32_bf16 v[74:77], v[180:183], v[204:207], v[74:77]
	v_mfma_f32_16x16x32_bf16 v[86:89], v[152:155], v[210:213], v[86:89]
	v_mfma_f32_16x16x32_bf16 v[86:89], v[156:159], v[214:217], v[86:89]
	v_mfma_f32_16x16x32_bf16 v[78:81], v[160:163], v[210:213], v[78:81]
	v_mfma_f32_16x16x32_bf16 v[78:81], v[164:167], v[214:217], v[78:81]
	v_mfma_f32_16x16x32_bf16 v[70:73], v[168:171], v[210:213], v[70:73]
	v_mfma_f32_16x16x32_bf16 v[70:73], v[172:175], v[214:217], v[70:73]
	v_mfma_f32_16x16x32_bf16 v[66:69], v[176:179], v[210:213], v[66:69]
	v_mfma_f32_16x16x32_bf16 v[66:69], v[180:183], v[214:217], v[66:69]
	s_setprio 0
	s_barrier
	s_add_i32 s62, s50, s37
	v_lshl_add_u64 v[144:145], s[30:31], 0, v[134:135]
	s_mov_b32 m0, s62
	ds_read_b128 v[184:187], v151 offset:16384
	ds_read_b128 v[188:191], v151 offset:17408
	ds_read_b128 v[192:195], v151 offset:18432
	ds_read_b128 v[196:199], v151 offset:19456
	ds_read_b128 v[200:203], v151 offset:20480
	ds_read_b128 v[204:207], v151 offset:21504
	ds_read_b128 v[210:213], v151 offset:22528
	ds_read_b128 v[214:217], v151 offset:23552
	global_load_lds_dwordx4 v[144:145], off
	s_add_i32 m0, s62, 0x2000
	s_add_u32 s62, s30, 0x80000
	v_lshl_add_u64 v[218:219], s[30:31], 0, v[130:131]
	s_addc_u32 s63, s31, 0
	s_add_i32 s64, s51, s37
	global_load_lds_dwordx4 v[218:219], off
	v_lshl_add_u64 v[220:221], s[62:63], 0, v[134:135]
	s_mov_b32 m0, s64
	v_lshl_add_u64 v[222:223], s[34:35], 0, v[132:133]
	global_load_lds_dwordx4 v[220:221], off
	v_lshl_add_u64 v[220:221], s[62:63], 0, v[130:131]
	s_add_i32 m0, s64, 0x2000
	s_nop 0
	global_load_lds_dwordx4 v[220:221], off
	v_lshl_add_u64 v[220:221], s[34:35], 0, v[136:137]
	s_mov_b32 m0, s27
	s_nop 0
	global_load_lds_dwordx4 v[220:221], off
	s_mov_b32 m0, s39
	s_nop 0
	global_load_lds_dwordx4 v[222:223], off
	s_waitcnt vmcnt(8)
	s_waitcnt lgkmcnt(0)
	s_barrier
; #define PG8_STAGE(bufoff, gbase, voff) do { _Pragma("unroll") for (int _i = 0; _i < 2; ++_i) \
;         __builtin_amdgcn_global_load_lds((const unsigned*)((const char*)(gbase) + (voff)[_i]), (PG8_LAS unsigned*)(lds + (bufoff) + ldsw + _i * 8192), 16, 0, 0); } while (0)
; #define PG8_LDA(dst, b, h) do { _Pragma("unroll") for (int m = 0; m < 4; ++m) _Pragma("unroll") for (int k = 0; k < 2; ++k) dst[m][k] = *(const PG8_LAS bf16x8*)(lds + PG8_SA(b, h) + aoff + m * 2048 + k * 1024); } while (0)
; #define PG8_LDB(dst, b, h) do { _Pragma("unroll") for (int n = 0; n < 2; ++n) _Pragma("unroll") for (int k = 0; k < 2; ++k) dst[n][k] = *(const PG8_LAS bf16x8*)(lds + PG8_SB(b, h) + boff + n * 2048 + k * 1024); } while (0)
; #define PG8_MMA(ai, bj, At, Bt) do { __builtin_amdgcn_s_setprio(1); _Pragma("unroll") for (int m = 0; m < 4; ++m) _Pragma("unroll") for (int n = 0; n < 2; ++n) _Pragma("unroll") for (int k = 0; k < 2; ++k) \
;         acc[ai][bj][m][n] = __builtin_amdgcn_mfma_f32_16x16x32_bf16(Bt[n][k], At[m][k], acc[ai][bj][m][n], 0, 0, 0); __builtin_amdgcn_s_setprio(0); } while (0)
; #define PG8_WAIT_V(n) asm volatile("s_waitcnt vmcnt(" #n ")" ::: "memory")
; #define PG8_WAIT_L(n) asm volatile("s_waitcnt lgkmcnt(" #n ")" ::: "memory")
; #define PG8_BAR __builtin_amdgcn_s_barrier()
; #define PG8_SCHED __builtin_amdgcn_sched_barrier(0)
; template <class Epi, class Sched, bool ALIGN_EPI = false, bool SP2 = false>
; __device__ __forceinline__ void gemm_phase(PG8_LAS unsigned char* lds, const Gemm g, const Sched& S, const Epi& E) {
;     ...
;             PG8_WAIT_V(8); PG8_WAIT_L(0); PG8_BAR; PG8_MMA(1, 0, At, B0); PG8_MMA(1, 1, At, B1); PG8_BAR; PG8_SCHED;
;             PG8_LDB(B0, 1, 0); PG8_LDB(B1, 1, 1); PG8_SCHED; PG8_LDA(At, 1, 0); PG8_STAGE(PG8_SA(0, 1), a2 + hstep, voffA);
;             PG8_WAIT_V(8); PG8_WAIT_L(0); PG8_BAR; PG8_MMA(0, 0, At, B0); PG8_MMA(0, 1, At, B1); PG8_BAR; PG8_SCHED;
;             PG8_LDA(At, 1, 1); PG8_STAGE(PG8_SB(1, 0), b3, voffB); PG8_STAGE(PG8_SB(1, 1), b3 + hstep, voffB); PG8_STAGE(PG8_SA(1, 0), a3, voffA);
	s_setprio 1
	s_waitcnt lgkmcnt(0)
	v_mfma_f32_16x16x32_bf16 v[62:65], v[152:155], v[184:187], v[62:65]
	v_mfma_f32_16x16x32_bf16 v[62:65], v[156:159], v[188:191], v[62:65]
	v_mfma_f32_16x16x32_bf16 v[58:61], v[160:163], v[184:187], v[58:61]
	v_mfma_f32_16x16x32_bf16 v[58:61], v[164:167], v[188:191], v[58:61]
	v_mfma_f32_16x16x32_bf16 v[50:53], v[168:171], v[184:187], v[50:53]
	v_mfma_f32_16x16x32_bf16 v[50:53], v[172:175], v[188:191], v[50:53]
	v_mfma_f32_16x16x32_bf16 v[42:45], v[176:179], v[184:187], v[42:45]
	v_mfma_f32_16x16x32_bf16 v[42:45], v[180:183], v[188:191], v[42:45]
	v_mfma_f32_16x16x32_bf16 v[54:57], v[152:155], v[192:195], v[54:57]
	v_mfma_f32_16x16x32_bf16 v[54:57], v[156:159], v[196:199], v[54:57]
	v_mfma_f32_16x16x32_bf16 v[46:49], v[160:163], v[192:195], v[46:49]
	v_mfma_f32_16x16x32_bf16 v[46:49], v[164:167], v[196:199], v[46:49]
	v_mfma_f32_16x16x32_bf16 v[34:37], v[168:171], v[192:195], v[34:37]
	v_mfma_f32_16x16x32_bf16 v[34:37], v[172:175], v[196:199], v[34:37]
	v_mfma_f32_16x16x32_bf16 v[26:29], v[176:179], v[192:195], v[26:29]
	v_mfma_f32_16x16x32_bf16 v[26:29], v[180:183], v[196:199], v[26:29]
	s_setprio 0
	s_setprio 1
	v_mfma_f32_16x16x32_bf16 v[38:41], v[152:155], v[200:203], v[38:41]
	v_mfma_f32_16x16x32_bf16 v[38:41], v[156:159], v[204:207], v[38:41]
	v_mfma_f32_16x16x32_bf16 v[30:33], v[160:163], v[200:203], v[30:33]
	v_mfma_f32_16x16x32_bf16 v[30:33], v[164:167], v[204:207], v[30:33]
	v_mfma_f32_16x16x32_bf16 v[18:21], v[168:171], v[200:203], v[18:21]
	v_mfma_f32_16x16x32_bf16 v[18:21], v[172:175], v[204:207], v[18:21]
	v_mfma_f32_16x16x32_bf16 v[10:13], v[176:179], v[200:203], v[10:13]
	v_mfma_f32_16x16x32_bf16 v[10:13], v[180:183], v[204:207], v[10:13]
	v_mfma_f32_16x16x32_bf16 v[22:25], v[152:155], v[210:213], v[22:25]
	v_mfma_f32_16x16x32_bf16 v[22:25], v[156:159], v[214:217], v[22:25]
	v_mfma_f32_16x16x32_bf16 v[14:17], v[160:163], v[210:213], v[14:17]
	v_mfma_f32_16x16x32_bf16 v[14:17], v[164:167], v[214:217], v[14:17]
	v_mfma_f32_16x16x32_bf16 v[6:9], v[168:171], v[210:213], v[6:9]
	v_mfma_f32_16x16x32_bf16 v[6:9], v[172:175], v[214:217], v[6:9]
	v_mfma_f32_16x16x32_bf16 v[2:5], v[176:179], v[210:213], v[2:5]
	v_mfma_f32_16x16x32_bf16 v[2:5], v[180:183], v[214:217], v[2:5]
	s_setprio 0
	s_barrier
	s_add_i32 s62, 0, 0x18000
	s_add_i32 s63, 0, 0x1c000
	v_add_u32_e32 v164, s62, v147
	v_add_u32_e32 v180, s63, v147
	ds_read_b128 v[152:155], v164
	ds_read_b128 v[156:159], v164 offset:1024
	ds_read_b128 v[160:163], v164 offset:2048
	ds_read_b128 v[164:167], v164 offset:3072
	ds_read_b128 v[168:171], v180
	ds_read_b128 v[172:175], v180 offset:1024
	ds_read_b128 v[176:179], v180 offset:2048
	ds_read_b128 v[180:183], v180 offset:3072
	s_add_u32 s34, s34, 0x80000
	s_addc_u32 s35, s35, 0
	s_mov_b32 m0, s40
	v_lshl_add_u64 v[224:225], s[34:35], 0, v[136:137]
	ds_read_b128 v[184:187], v151 offset:32768
	ds_read_b128 v[188:191], v151 offset:33792
	ds_read_b128 v[192:195], v151 offset:34816
	ds_read_b128 v[196:199], v151 offset:35840
	ds_read_b128 v[200:203], v151 offset:36864
	ds_read_b128 v[204:207], v151 offset:37888
	ds_read_b128 v[210:213], v151 offset:38912
	ds_read_b128 v[214:217], v151 offset:39936
	global_load_lds_dwordx4 v[224:225], off
	v_lshl_add_u64 v[224:225], s[34:35], 0, v[132:133]
	s_mov_b32 m0, s41
	s_nop 0
	global_load_lds_dwordx4 v[224:225], off
	s_waitcnt vmcnt(8)
	s_waitcnt lgkmcnt(0)
	s_barrier
	s_setprio 1
	s_waitcnt lgkmcnt(0)
	v_mfma_f32_16x16x32_bf16 v[126:129], v[152:155], v[184:187], v[126:129]
	v_mfma_f32_16x16x32_bf16 v[126:129], v[156:159], v[188:191], v[126:129]
	v_mfma_f32_16x16x32_bf16 v[122:125], v[160:163], v[184:187], v[122:125]
	v_mfma_f32_16x16x32_bf16 v[122:125], v[164:167], v[188:191], v[122:125]
	v_mfma_f32_16x16x32_bf16 v[114:117], v[168:171], v[184:187], v[114:117]
	v_mfma_f32_16x16x32_bf16 v[114:117], v[172:175], v[188:191], v[114:117]
	v_mfma_f32_16x16x32_bf16 v[106:109], v[176:179], v[184:187], v[106:109]
	v_mfma_f32_16x16x32_bf16 v[106:109], v[180:183], v[188:191], v[106:109]
	v_mfma_f32_16x16x32_bf16 v[118:121], v[152:155], v[192:195], v[118:121]
	v_mfma_f32_16x16x32_bf16 v[118:121], v[156:159], v[196:199], v[118:121]
	v_mfma_f32_16x16x32_bf16 v[110:113], v[160:163], v[192:195], v[110:113]
	v_mfma_f32_16x16x32_bf16 v[110:113], v[164:167], v[196:199], v[110:113]
	v_mfma_f32_16x16x32_bf16 v[98:101], v[168:171], v[192:195], v[98:101]
	v_mfma_f32_16x16x32_bf16 v[98:101], v[172:175], v[196:199], v[98:101]
	v_mfma_f32_16x16x32_bf16 v[90:93], v[176:179], v[192:195], v[90:93]
	v_mfma_f32_16x16x32_bf16 v[90:93], v[180:183], v[196:199], v[90:93]
	s_setprio 0
	s_setprio 1
	v_mfma_f32_16x16x32_bf16 v[102:105], v[152:155], v[200:203], v[102:105]
	v_mfma_f32_16x16x32_bf16 v[102:105], v[156:159], v[204:207], v[102:105]
	v_mfma_f32_16x16x32_bf16 v[94:97], v[160:163], v[200:203], v[94:97]
	v_mfma_f32_16x16x32_bf16 v[94:97], v[164:167], v[204:207], v[94:97]
	v_mfma_f32_16x16x32_bf16 v[82:85], v[168:171], v[200:203], v[82:85]
	v_mfma_f32_16x16x32_bf16 v[82:85], v[172:175], v[204:207], v[82:85]
	v_mfma_f32_16x16x32_bf16 v[74:77], v[176:179], v[200:203], v[74:77]
	v_mfma_f32_16x16x32_bf16 v[74:77], v[180:183], v[204:207], v[74:77]
	v_mfma_f32_16x16x32_bf16 v[86:89], v[152:155], v[210:213], v[86:89]
	v_mfma_f32_16x16x32_bf16 v[86:89], v[156:159], v[214:217], v[86:89]
	v_mfma_f32_16x16x32_bf16 v[78:81], v[160:163], v[210:213], v[78:81]
	v_mfma_f32_16x16x32_bf16 v[78:81], v[164:167], v[214:217], v[78:81]
	v_mfma_f32_16x16x32_bf16 v[70:73], v[168:171], v[210:213], v[70:73]
	v_mfma_f32_16x16x32_bf16 v[70:73], v[172:175], v[214:217], v[70:73]
	v_mfma_f32_16x16x32_bf16 v[66:69], v[176:179], v[210:213], v[66:69]
	v_mfma_f32_16x16x32_bf16 v[66:69], v[180:183], v[214:217], v[66:69]
	s_setprio 0
	s_barrier
; #define PG8_STAGE(bufoff, gbase, voff) do { _Pragma("unroll") for (int _i = 0; _i < 2; ++_i) \
;         __builtin_amdgcn_global_load_lds((const unsigned*)((const char*)(gbase) + (voff)[_i]), (PG8_LAS unsigned*)(lds + (bufoff) + ldsw + _i * 8192), 16, 0, 0); } while (0)
; #define PG8_LDA(dst, b, h) do { _Pragma("unroll") for (int m = 0; m < 4; ++m) _Pragma("unroll") for (int k = 0; k < 2; ++k) dst[m][k] = *(const PG8_LAS bf16x8*)(lds + PG8_SA(b, h) + aoff + m * 2048 + k * 1024); } while (0)
; #define PG8_MMA(ai, bj, At, Bt) do { __builtin_amdgcn_s_setprio(1); _Pragma("unroll") for (int m = 0; m < 4; ++m) _Pragma("unroll") for (int n = 0; n < 2; ++n) _Pragma("unroll") for (int k = 0; k < 2; ++k) \
;         acc[ai][bj][m][n] = __builtin_amdgcn_mfma_f32_16x16x32_bf16(Bt[n][k], At[m][k], acc[ai][bj][m][n], 0, 0, 0); __builtin_amdgcn_s_setprio(0); } while (0)
; #define PG8_WAIT_V(n) asm volatile("s_waitcnt vmcnt(" #n ")" ::: "memory")
; #define PG8_WAIT_L(n) asm volatile("s_waitcnt lgkmcnt(" #n ")" ::: "memory")
; #define PG8_BAR __builtin_amdgcn_s_barrier()
; #define PG8_SCHED __builtin_amdgcn_sched_barrier(0)
; template <class Epi, class Sched, bool ALIGN_EPI = false, bool SP2 = false>
; __device__ __forceinline__ void gemm_phase(PG8_LAS unsigned char* lds, const Gemm g, const Sched& S, const Epi& E) {
;     ...
;         for (int t = 0; t < nt; t += 2) {
;             const bool last = (t == nt - 2);
;             const char* a1 = cA + (size_t)(t + 1) * kstep;
;             const char* a2 = last ? nA : cA + (size_t)(t + 2) * kstep; const char* b2 = last ? nB : cB + (size_t)(t + 2) * kstep;
;     ...
;             PG8_LDA(At, 1, 1); PG8_STAGE(PG8_SB(1, 0), b3, voffB); PG8_STAGE(PG8_SB(1, 1), b3 + hstep, voffB); PG8_STAGE(PG8_SA(1, 0), a3, voffA);
;             PG8_WAIT_V(8); PG8_WAIT_L(0); PG8_BAR; PG8_MMA(1, 0, At, B0); PG8_MMA(1, 1, At, B1); PG8_BAR; PG8_SCHED;
;     ...
;         if constexpr (ALIGN_EPI) { if (wr == 0) PG8_BAR; }
	s_add_i32 s34, s62, s37
	v_lshl_add_u64 v[144:145], v[144:145], 0, s[6:7]
	s_mov_b32 m0, s34
	ds_read_b128 v[184:187], v151 offset:49152
	ds_read_b128 v[188:191], v151 offset:50176
	ds_read_b128 v[192:195], v151 offset:51200
	ds_read_b128 v[196:199], v151 offset:52224
	ds_read_b128 v[200:203], v151 offset:53248
	ds_read_b128 v[204:207], v151 offset:54272
	ds_read_b128 v[210:213], v151 offset:55296
	ds_read_b128 v[214:217], v151 offset:56320
	global_load_lds_dwordx4 v[144:145], off
	s_add_i32 m0, s34, 0x2000
	s_add_u32 s30, s30, 0x80080
	v_lshl_add_u64 v[144:145], v[218:219], 0, s[6:7]
	s_addc_u32 s31, s31, 0
	s_add_i32 s34, s63, s37
	global_load_lds_dwordx4 v[144:145], off
	v_lshl_add_u64 v[144:145], s[30:31], 0, v[134:135]
	s_mov_b32 m0, s34
	s_nop 0
	global_load_lds_dwordx4 v[144:145], off
	v_lshl_add_u64 v[144:145], s[30:31], 0, v[130:131]
	s_add_i32 m0, s34, 0x2000
	s_nop 0
	global_load_lds_dwordx4 v[144:145], off
	v_lshl_add_u64 v[144:145], v[220:221], 0, s[6:7]
	s_mov_b32 m0, s48
	s_nop 0
	global_load_lds_dwordx4 v[144:145], off
	v_lshl_add_u64 v[144:145], v[222:223], 0, s[6:7]
	s_mov_b32 m0, s49
	s_nop 0
	global_load_lds_dwordx4 v[144:145], off
	s_waitcnt vmcnt(8)
	s_waitcnt lgkmcnt(0)
	s_barrier
	s_setprio 1
	s_waitcnt lgkmcnt(0)
	v_mfma_f32_16x16x32_bf16 v[62:65], v[152:155], v[184:187], v[62:65]
	v_mfma_f32_16x16x32_bf16 v[62:65], v[156:159], v[188:191], v[62:65]
	v_mfma_f32_16x16x32_bf16 v[58:61], v[160:163], v[184:187], v[58:61]
	v_mfma_f32_16x16x32_bf16 v[58:61], v[164:167], v[188:191], v[58:61]
	v_mfma_f32_16x16x32_bf16 v[50:53], v[168:171], v[184:187], v[50:53]
	v_mfma_f32_16x16x32_bf16 v[50:53], v[172:175], v[188:191], v[50:53]
	v_mfma_f32_16x16x32_bf16 v[42:45], v[176:179], v[184:187], v[42:45]
	v_mfma_f32_16x16x32_bf16 v[42:45], v[180:183], v[188:191], v[42:45]
	v_mfma_f32_16x16x32_bf16 v[54:57], v[152:155], v[192:195], v[54:57]
	v_mfma_f32_16x16x32_bf16 v[54:57], v[156:159], v[196:199], v[54:57]
	v_mfma_f32_16x16x32_bf16 v[46:49], v[160:163], v[192:195], v[46:49]
	v_mfma_f32_16x16x32_bf16 v[46:49], v[164:167], v[196:199], v[46:49]
	v_mfma_f32_16x16x32_bf16 v[34:37], v[168:171], v[192:195], v[34:37]
	v_mfma_f32_16x16x32_bf16 v[34:37], v[172:175], v[196:199], v[34:37]
	v_mfma_f32_16x16x32_bf16 v[26:29], v[176:179], v[192:195], v[26:29]
	v_mfma_f32_16x16x32_bf16 v[26:29], v[180:183], v[196:199], v[26:29]
	s_setprio 0
	s_setprio 1
	v_mfma_f32_16x16x32_bf16 v[38:41], v[152:155], v[200:203], v[38:41]
	v_mfma_f32_16x16x32_bf16 v[38:41], v[156:159], v[204:207], v[38:41]
	v_mfma_f32_16x16x32_bf16 v[30:33], v[160:163], v[200:203], v[30:33]
	v_mfma_f32_16x16x32_bf16 v[30:33], v[164:167], v[204:207], v[30:33]
	v_mfma_f32_16x16x32_bf16 v[18:21], v[168:171], v[200:203], v[18:21]
	v_mfma_f32_16x16x32_bf16 v[18:21], v[172:175], v[204:207], v[18:21]
	v_mfma_f32_16x16x32_bf16 v[10:13], v[176:179], v[200:203], v[10:13]
	v_mfma_f32_16x16x32_bf16 v[10:13], v[180:183], v[204:207], v[10:13]
	v_mfma_f32_16x16x32_bf16 v[22:25], v[152:155], v[210:213], v[22:25]
	v_mfma_f32_16x16x32_bf16 v[22:25], v[156:159], v[214:217], v[22:25]
	v_mfma_f32_16x16x32_bf16 v[14:17], v[160:163], v[210:213], v[14:17]
	v_mfma_f32_16x16x32_bf16 v[14:17], v[164:167], v[214:217], v[14:17]
	v_mfma_f32_16x16x32_bf16 v[6:9], v[168:171], v[210:213], v[6:9]
	v_mfma_f32_16x16x32_bf16 v[6:9], v[172:175], v[214:217], v[6:9]
	v_mfma_f32_16x16x32_bf16 v[2:5], v[176:179], v[210:213], v[2:5]
	v_mfma_f32_16x16x32_bf16 v[2:5], v[180:183], v[214:217], v[2:5]
	s_setprio 0
	s_barrier
	s_add_i32 s61, s61, 2
	s_add_u32 s28, s28, 0x100
	s_addc_u32 s29, s29, 0
	s_add_u32 s59, s59, 0x100
	s_addc_u32 s60, s60, 0
	s_cmp_gt_u32 s61, 29
	s_cbranch_scc0 .LBB11_228
	s_and_b64 vcc, exec, s[8:9]
	s_cbranch_vccz .LBB11_231
	s_barrier

; #define PG8_STAGE(bufoff, gbase, voff) do { _Pragma("unroll") for (int _i = 0; _i < 2; ++_i) \
;         __builtin_amdgcn_global_load_lds((const unsigned*)((const char*)(gbase) + (voff)[_i]), (PG8_LAS unsigned*)(lds + (bufoff) + ldsw + _i * 8192), 16, 0, 0); } while (0)
; #define PG8_LDA(dst, b, h) do { _Pragma("unroll") for (int m = 0; m < 4; ++m) _Pragma("unroll") for (int k = 0; k < 2; ++k) dst[m][k] = *(const PG8_LAS bf16x8*)(lds + PG8_SA(b, h) + aoff + m * 2048 + k * 1024); } while (0)
; #define PG8_LDB(dst, b, h) do { _Pragma("unroll") for (int n = 0; n < 2; ++n) _Pragma("unroll") for (int k = 0; k < 2; ++k) dst[n][k] = *(const PG8_LAS bf16x8*)(lds + PG8_SB(b, h) + boff + n * 2048 + k * 1024); } while (0)
; #define PG8_WAIT_V(n) asm volatile("s_waitcnt vmcnt(" #n ")" ::: "memory")
; #define PG8_WAIT_L(n) asm volatile("s_waitcnt lgkmcnt(" #n ")" ::: "memory")
; #define PG8_BAR __builtin_amdgcn_s_barrier()
; #define PG8_SCHED __builtin_amdgcn_sched_barrier(0)
; template <class Epi, class Sched, bool ALIGN_EPI = false, bool SP2 = false>
; __device__ __forceinline__ void gemm_phase(PG8_LAS unsigned char* lds, const Gemm g, const Sched& S, const Epi& E) {
;     ...
;         const char* nA = has_next ? (const char*)g.A + (size_t)nxt.pm * tstep : cA; const char* nB = has_next ? (const char*)g.Bt + (size_t)nxt.pn * tstep : cB;
;         for (int t = 0; t < nt; t += 2) {
;             const bool last = (t == nt - 2);
;             const char* a1 = cA + (size_t)(t + 1) * kstep;
;             const char* a2 = last ? nA : cA + (size_t)(t + 2) * kstep; const char* b2 = last ? nB : cB + (size_t)(t + 2) * kstep;
;             const char* a3 = a2 + kstep; const char* b3 = b2 + kstep;
;             if (last && has_next) S.a_ready(nxt);
;             if constexpr (SP2) {
;             PG8_LDB(B0, 0, 0); PG8_LDB(B1, 0, 1); PG8_SCHED; PG8_LDA(At, 0, 0); PG8_STAGE(PG8_SA(1, 1), a1 + hstep, voffA);
;             PG8_WAIT_V(8); PG8_WAIT_L(0); PG8_BAR; PG8_MMA(0, 0, At, B0); PG8_MMA(0, 1, At, B1); PG8_BAR; PG8_SCHED;
;             PG8_LDA(At, 0, 1); PG8_STAGE(PG8_SB(0, 0), b2, voffB); PG8_STAGE(PG8_SB(0, 1), b2 + hstep, voffB); PG8_STAGE(PG8_SA(0, 0), a2, voffA);
;             PG8_WAIT_V(8); PG8_WAIT_L(0); PG8_BAR; PG8_MMA(1, 0, At, B0); PG8_MMA(1, 1, At, B1); PG8_BAR; PG8_SCHED;
.LBB11_456:
	s_add_u32 s18, s16, 0xfff80080
	s_addc_u32 s19, s17, -1
	s_add_i32 s49, 0, 0x10000
	s_cmp_eq_u32 s48, 28
	s_cselect_b32 s21, s11, s19
	s_cselect_b32 s20, s44, s18
	v_add_u32_e32 v144, s49, v147
	s_cselect_b32 s19, s9, s47
	s_cselect_b32 s18, s45, s46
	s_add_i32 s52, 0, 0x14000
	ds_read_b128 v[150:153], v144
	ds_read_b128 v[154:157], v144 offset:1024
	ds_read_b128 v[158:161], v144 offset:2048
	ds_read_b128 v[162:165], v144 offset:3072
	v_add_u32_e32 v144, s52, v147
	ds_read_b128 v[166:169], v144
	ds_read_b128 v[170:173], v144 offset:1024
	ds_read_b128 v[174:177], v144 offset:2048
	ds_read_b128 v[178:181], v144 offset:3072
	v_lshl_add_u64 v[144:145], s[16:17], 0, v[140:141]
	s_add_i32 m0, s29, 0xc000
	ds_read_b128 v[198:201], v149
	ds_read_b128 v[202:205], v149 offset:1024
	ds_read_b128 v[220:223], v149 offset:2048
	ds_read_b128 v[224:227], v149 offset:3072
	ds_read_b128 v[228:231], v149 offset:4096
	ds_read_b128 v[232:235], v149 offset:5120
	ds_read_b128 v[236:239], v149 offset:6144
	ds_read_b128 v[240:243], v149 offset:7168
	global_load_lds_dwordx4 v[144:145], off
	v_lshl_add_u64 v[144:145], s[16:17], 0, v[142:143]
	s_add_i32 m0, s29, 0xe000
	s_nop 0
	global_load_lds_dwordx4 v[144:145], off
	s_waitcnt vmcnt(8)
	s_waitcnt lgkmcnt(0)
	s_barrier
	s_setprio 1
	s_waitcnt lgkmcnt(0)
	v_mfma_f32_16x16x32_bf16 v[124:127], v[150:153], v[198:201], v[124:127]
	v_mfma_f32_16x16x32_bf16 v[124:127], v[154:157], v[202:205], v[124:127]
	v_mfma_f32_16x16x32_bf16 v[116:119], v[158:161], v[198:201], v[116:119]
	v_mfma_f32_16x16x32_bf16 v[116:119], v[162:165], v[202:205], v[116:119]
	v_mfma_f32_16x16x32_bf16 v[128:131], v[166:169], v[198:201], v[128:131]
	v_mfma_f32_16x16x32_bf16 v[128:131], v[170:173], v[202:205], v[128:131]
	v_mfma_f32_16x16x32_bf16 v[120:123], v[174:177], v[198:201], v[120:123]
	v_mfma_f32_16x16x32_bf16 v[120:123], v[178:181], v[202:205], v[120:123]
	v_mfma_f32_16x16x32_bf16 v[108:111], v[150:153], v[220:223], v[108:111]
	v_mfma_f32_16x16x32_bf16 v[108:111], v[154:157], v[224:227], v[108:111]
	v_mfma_f32_16x16x32_bf16 v[100:103], v[158:161], v[220:223], v[100:103]
	v_mfma_f32_16x16x32_bf16 v[100:103], v[162:165], v[224:227], v[100:103]
	v_mfma_f32_16x16x32_bf16 v[112:115], v[166:169], v[220:223], v[112:115]
	v_mfma_f32_16x16x32_bf16 v[112:115], v[170:173], v[224:227], v[112:115]
	v_mfma_f32_16x16x32_bf16 v[104:107], v[174:177], v[220:223], v[104:107]
	v_mfma_f32_16x16x32_bf16 v[104:107], v[178:181], v[224:227], v[104:107]
	s_setprio 0
	s_setprio 1
	v_mfma_f32_16x16x32_bf16 v[92:95], v[150:153], v[228:231], v[92:95]
	v_mfma_f32_16x16x32_bf16 v[92:95], v[154:157], v[232:235], v[92:95]
	v_mfma_f32_16x16x32_bf16 v[84:87], v[158:161], v[228:231], v[84:87]
	v_mfma_f32_16x16x32_bf16 v[84:87], v[162:165], v[232:235], v[84:87]
	v_mfma_f32_16x16x32_bf16 v[96:99], v[166:169], v[228:231], v[96:99]
	v_mfma_f32_16x16x32_bf16 v[96:99], v[170:173], v[232:235], v[96:99]
	v_mfma_f32_16x16x32_bf16 v[88:91], v[174:177], v[228:231], v[88:91]
	v_mfma_f32_16x16x32_bf16 v[88:91], v[178:181], v[232:235], v[88:91]
	v_mfma_f32_16x16x32_bf16 v[76:79], v[150:153], v[236:239], v[76:79]
	v_mfma_f32_16x16x32_bf16 v[76:79], v[154:157], v[240:243], v[76:79]
	v_mfma_f32_16x16x32_bf16 v[68:71], v[158:161], v[236:239], v[68:71]
	v_mfma_f32_16x16x32_bf16 v[68:71], v[162:165], v[240:243], v[68:71]
	v_mfma_f32_16x16x32_bf16 v[80:83], v[166:169], v[236:239], v[80:83]
	v_mfma_f32_16x16x32_bf16 v[80:83], v[170:173], v[240:243], v[80:83]
	v_mfma_f32_16x16x32_bf16 v[72:75], v[174:177], v[236:239], v[72:75]
	v_mfma_f32_16x16x32_bf16 v[72:75], v[178:181], v[240:243], v[72:75]
	s_setprio 0
	s_barrier
	s_add_i32 s49, s49, s27
	v_lshl_add_u64 v[144:145], s[18:19], 0, v[2:3]
	s_mov_b32 m0, s49
	ds_read_b128 v[198:201], v149 offset:16384
	ds_read_b128 v[202:205], v149 offset:17408
	ds_read_b128 v[220:223], v149 offset:18432
	ds_read_b128 v[224:227], v149 offset:19456
	ds_read_b128 v[228:231], v149 offset:20480
	ds_read_b128 v[232:235], v149 offset:21504
	ds_read_b128 v[236:239], v149 offset:22528
	ds_read_b128 v[240:243], v149 offset:23552
	global_load_lds_dwordx4 v[144:145], off
	s_add_i32 m0, s49, 0x2000
	s_add_u32 s50, s18, 0x80000
	v_lshl_add_u64 v[206:207], s[18:19], 0, v[132:133]
	s_addc_u32 s51, s19, 0
	s_add_i32 s49, s52, s27
	global_load_lds_dwordx4 v[206:207], off
	v_lshl_add_u64 v[244:245], s[50:51], 0, v[2:3]
	s_mov_b32 m0, s49
	v_lshl_add_u64 v[246:247], s[20:21], 0, v[134:135]
	global_load_lds_dwordx4 v[244:245], off
	v_lshl_add_u64 v[244:245], s[50:51], 0, v[132:133]
	s_add_i32 m0, s49, 0x2000
	s_nop 0
	global_load_lds_dwordx4 v[244:245], off
	v_lshl_add_u64 v[244:245], s[20:21], 0, v[136:137]
	s_mov_b32 m0, s29
	s_nop 0
	global_load_lds_dwordx4 v[244:245], off
	s_mov_b32 m0, s30
	s_nop 0
	global_load_lds_dwordx4 v[246:247], off
	s_waitcnt vmcnt(8)
	s_waitcnt lgkmcnt(0)
	s_barrier
; #define PG8_STAGE(bufoff, gbase, voff) do { _Pragma("unroll") for (int _i = 0; _i < 2; ++_i) \
;         __builtin_amdgcn_global_load_lds((const unsigned*)((const char*)(gbase) + (voff)[_i]), (PG8_LAS unsigned*)(lds + (bufoff) + ldsw + _i * 8192), 16, 0, 0); } while (0)
; #define PG8_LDA(dst, b, h) do { _Pragma("unroll") for (int m = 0; m < 4; ++m) _Pragma("unroll") for (int k = 0; k < 2; ++k) dst[m][k] = *(const PG8_LAS bf16x8*)(lds + PG8_SA(b, h) + aoff + m * 2048 + k * 1024); } while (0)
; #define PG8_LDB(dst, b, h) do { _Pragma("unroll") for (int n = 0; n < 2; ++n) _Pragma("unroll") for (int k = 0; k < 2; ++k) dst[n][k] = *(const PG8_LAS bf16x8*)(lds + PG8_SB(b, h) + boff + n * 2048 + k * 1024); } while (0)
; #define PG8_MMA(ai, bj, At, Bt) do { __builtin_amdgcn_s_setprio(1); _Pragma("unroll") for (int m = 0; m < 4; ++m) _Pragma("unroll") for (int n = 0; n < 2; ++n) _Pragma("unroll") for (int k = 0; k < 2; ++k) \
;         acc[ai][bj][m][n] = __builtin_amdgcn_mfma_f32_16x16x32_bf16(Bt[n][k], At[m][k], acc[ai][bj][m][n], 0, 0, 0); __builtin_amdgcn_s_setprio(0); } while (0)
; #define PG8_WAIT_V(n) asm volatile("s_waitcnt vmcnt(" #n ")" ::: "memory")
; #define PG8_WAIT_L(n) asm volatile("s_waitcnt lgkmcnt(" #n ")" ::: "memory")
; #define PG8_BAR __builtin_amdgcn_s_barrier()
; #define PG8_SCHED __builtin_amdgcn_sched_barrier(0)
; template <class Epi, class Sched, bool ALIGN_EPI = false, bool SP2 = false>
; __device__ __forceinline__ void gemm_phase(PG8_LAS unsigned char* lds, const Gemm g, const Sched& S, const Epi& E) {
;     ...
;             PG8_WAIT_V(8); PG8_WAIT_L(0); PG8_BAR; PG8_MMA(1, 0, At, B0); PG8_MMA(1, 1, At, B1); PG8_BAR; PG8_SCHED;
;             PG8_LDB(B0, 1, 0); PG8_LDB(B1, 1, 1); PG8_SCHED; PG8_LDA(At, 1, 0); PG8_STAGE(PG8_SA(0, 1), a2 + hstep, voffA);
;             PG8_WAIT_V(8); PG8_WAIT_L(0); PG8_BAR; PG8_MMA(0, 0, At, B0); PG8_MMA(0, 1, At, B1); PG8_BAR; PG8_SCHED;
;             PG8_LDA(At, 1, 1); PG8_STAGE(PG8_SB(1, 0), b3, voffB); PG8_STAGE(PG8_SB(1, 1), b3 + hstep, voffB); PG8_STAGE(PG8_SA(1, 0), a3, voffA);
	s_setprio 1
	s_waitcnt lgkmcnt(0)
	v_mfma_f32_16x16x32_bf16 v[60:63], v[150:153], v[198:201], v[60:63]
	v_mfma_f32_16x16x32_bf16 v[60:63], v[154:157], v[202:205], v[60:63]
	v_mfma_f32_16x16x32_bf16 v[52:55], v[158:161], v[198:201], v[52:55]
	v_mfma_f32_16x16x32_bf16 v[52:55], v[162:165], v[202:205], v[52:55]
	v_mfma_f32_16x16x32_bf16 v[64:67], v[166:169], v[198:201], v[64:67]
	v_mfma_f32_16x16x32_bf16 v[64:67], v[170:173], v[202:205], v[64:67]
	v_mfma_f32_16x16x32_bf16 v[56:59], v[174:177], v[198:201], v[56:59]
	v_mfma_f32_16x16x32_bf16 v[56:59], v[178:181], v[202:205], v[56:59]
	v_mfma_f32_16x16x32_bf16 v[44:47], v[150:153], v[220:223], v[44:47]
	v_mfma_f32_16x16x32_bf16 v[44:47], v[154:157], v[224:227], v[44:47]
	v_mfma_f32_16x16x32_bf16 v[36:39], v[158:161], v[220:223], v[36:39]
	v_mfma_f32_16x16x32_bf16 v[36:39], v[162:165], v[224:227], v[36:39]
	v_mfma_f32_16x16x32_bf16 v[48:51], v[166:169], v[220:223], v[48:51]
	v_mfma_f32_16x16x32_bf16 v[48:51], v[170:173], v[224:227], v[48:51]
	v_mfma_f32_16x16x32_bf16 v[40:43], v[174:177], v[220:223], v[40:43]
	v_mfma_f32_16x16x32_bf16 v[40:43], v[178:181], v[224:227], v[40:43]
	s_setprio 0
	s_setprio 1
	v_mfma_f32_16x16x32_bf16 v[28:31], v[150:153], v[228:231], v[28:31]
	v_mfma_f32_16x16x32_bf16 v[28:31], v[154:157], v[232:235], v[28:31]
	v_mfma_f32_16x16x32_bf16 v[20:23], v[158:161], v[228:231], v[20:23]
	v_mfma_f32_16x16x32_bf16 v[20:23], v[162:165], v[232:235], v[20:23]
	v_mfma_f32_16x16x32_bf16 v[32:35], v[166:169], v[228:231], v[32:35]
	v_mfma_f32_16x16x32_bf16 v[32:35], v[170:173], v[232:235], v[32:35]
	v_mfma_f32_16x16x32_bf16 v[24:27], v[174:177], v[228:231], v[24:27]
	v_mfma_f32_16x16x32_bf16 v[24:27], v[178:181], v[232:235], v[24:27]
	v_mfma_f32_16x16x32_bf16 v[12:15], v[150:153], v[236:239], v[12:15]
	v_mfma_f32_16x16x32_bf16 v[12:15], v[154:157], v[240:243], v[12:15]
	v_mfma_f32_16x16x32_bf16 v[4:7], v[158:161], v[236:239], v[4:7]
	v_mfma_f32_16x16x32_bf16 v[4:7], v[162:165], v[240:243], v[4:7]
	v_mfma_f32_16x16x32_bf16 v[16:19], v[166:169], v[236:239], v[16:19]
	v_mfma_f32_16x16x32_bf16 v[16:19], v[170:173], v[240:243], v[16:19]
	v_mfma_f32_16x16x32_bf16 v[8:11], v[174:177], v[236:239], v[8:11]
	v_mfma_f32_16x16x32_bf16 v[8:11], v[178:181], v[240:243], v[8:11]
	s_setprio 0
	s_barrier
	s_add_i32 s49, 0, 0x18000
	s_add_i32 s50, 0, 0x1c000
	v_add_u32_e32 v162, s49, v147
	v_add_u32_e32 v178, s50, v147
	ds_read_b128 v[150:153], v162
	ds_read_b128 v[154:157], v162 offset:1024
	ds_read_b128 v[158:161], v162 offset:2048
	ds_read_b128 v[162:165], v162 offset:3072
	ds_read_b128 v[166:169], v178
	ds_read_b128 v[170:173], v178 offset:1024
	ds_read_b128 v[174:177], v178 offset:2048
	ds_read_b128 v[178:181], v178 offset:3072
	s_add_u32 s20, s20, 0x80000
	s_addc_u32 s21, s21, 0
	s_mov_b32 m0, s33
	v_lshl_add_u64 v[196:197], s[20:21], 0, v[136:137]
	ds_read_b128 v[198:201], v149 offset:32768
	ds_read_b128 v[202:205], v149 offset:33792
	ds_read_b128 v[220:223], v149 offset:34816
	ds_read_b128 v[224:227], v149 offset:35840
	ds_read_b128 v[228:231], v149 offset:36864
	ds_read_b128 v[232:235], v149 offset:37888
	ds_read_b128 v[236:239], v149 offset:38912
	ds_read_b128 v[240:243], v149 offset:39936
	global_load_lds_dwordx4 v[196:197], off
	v_lshl_add_u64 v[196:197], s[20:21], 0, v[134:135]
	s_mov_b32 m0, s38
	s_nop 0
	global_load_lds_dwordx4 v[196:197], off
	s_waitcnt vmcnt(8)
	s_waitcnt lgkmcnt(0)
	s_barrier
	s_setprio 1
	s_waitcnt lgkmcnt(0)
	v_mfma_f32_16x16x32_bf16 v[124:127], v[150:153], v[198:201], v[124:127]
	v_mfma_f32_16x16x32_bf16 v[124:127], v[154:157], v[202:205], v[124:127]
	v_mfma_f32_16x16x32_bf16 v[116:119], v[158:161], v[198:201], v[116:119]
	v_mfma_f32_16x16x32_bf16 v[116:119], v[162:165], v[202:205], v[116:119]
	v_mfma_f32_16x16x32_bf16 v[128:131], v[166:169], v[198:201], v[128:131]
	v_mfma_f32_16x16x32_bf16 v[128:131], v[170:173], v[202:205], v[128:131]
	v_mfma_f32_16x16x32_bf16 v[120:123], v[174:177], v[198:201], v[120:123]
	v_mfma_f32_16x16x32_bf16 v[120:123], v[178:181], v[202:205], v[120:123]
	v_mfma_f32_16x16x32_bf16 v[108:111], v[150:153], v[220:223], v[108:111]
	v_mfma_f32_16x16x32_bf16 v[108:111], v[154:157], v[224:227], v[108:111]
	v_mfma_f32_16x16x32_bf16 v[100:103], v[158:161], v[220:223], v[100:103]
	v_mfma_f32_16x16x32_bf16 v[100:103], v[162:165], v[224:227], v[100:103]
	v_mfma_f32_16x16x32_bf16 v[112:115], v[166:169], v[220:223], v[112:115]
	v_mfma_f32_16x16x32_bf16 v[112:115], v[170:173], v[224:227], v[112:115]
	v_mfma_f32_16x16x32_bf16 v[104:107], v[174:177], v[220:223], v[104:107]
	v_mfma_f32_16x16x32_bf16 v[104:107], v[178:181], v[224:227], v[104:107]
	s_setprio 0
	s_setprio 1
	v_mfma_f32_16x16x32_bf16 v[92:95], v[150:153], v[228:231], v[92:95]
	v_mfma_f32_16x16x32_bf16 v[92:95], v[154:157], v[232:235], v[92:95]
	v_mfma_f32_16x16x32_bf16 v[84:87], v[158:161], v[228:231], v[84:87]
	v_mfma_f32_16x16x32_bf16 v[84:87], v[162:165], v[232:235], v[84:87]
	v_mfma_f32_16x16x32_bf16 v[96:99], v[166:169], v[228:231], v[96:99]
	v_mfma_f32_16x16x32_bf16 v[96:99], v[170:173], v[232:235], v[96:99]
	v_mfma_f32_16x16x32_bf16 v[88:91], v[174:177], v[228:231], v[88:91]
	v_mfma_f32_16x16x32_bf16 v[88:91], v[178:181], v[232:235], v[88:91]
	v_mfma_f32_16x16x32_bf16 v[76:79], v[150:153], v[236:239], v[76:79]
	v_mfma_f32_16x16x32_bf16 v[76:79], v[154:157], v[240:243], v[76:79]
	v_mfma_f32_16x16x32_bf16 v[68:71], v[158:161], v[236:239], v[68:71]
	v_mfma_f32_16x16x32_bf16 v[68:71], v[162:165], v[240:243], v[68:71]
	v_mfma_f32_16x16x32_bf16 v[80:83], v[166:169], v[236:239], v[80:83]
	v_mfma_f32_16x16x32_bf16 v[80:83], v[170:173], v[240:243], v[80:83]
	v_mfma_f32_16x16x32_bf16 v[72:75], v[174:177], v[236:239], v[72:75]
	v_mfma_f32_16x16x32_bf16 v[72:75], v[178:181], v[240:243], v[72:75]
	s_setprio 0
	s_barrier
; #define PG8_STAGE(bufoff, gbase, voff) do { _Pragma("unroll") for (int _i = 0; _i < 2; ++_i) \
;         __builtin_amdgcn_global_load_lds((const unsigned*)((const char*)(gbase) + (voff)[_i]), (PG8_LAS unsigned*)(lds + (bufoff) + ldsw + _i * 8192), 16, 0, 0); } while (0)
; #define PG8_LDA(dst, b, h) do { _Pragma("unroll") for (int m = 0; m < 4; ++m) _Pragma("unroll") for (int k = 0; k < 2; ++k) dst[m][k] = *(const PG8_LAS bf16x8*)(lds + PG8_SA(b, h) + aoff + m * 2048 + k * 1024); } while (0)
; #define PG8_MMA(ai, bj, At, Bt) do { __builtin_amdgcn_s_setprio(1); _Pragma("unroll") for (int m = 0; m < 4; ++m) _Pragma("unroll") for (int n = 0; n < 2; ++n) _Pragma("unroll") for (int k = 0; k < 2; ++k) \
;         acc[ai][bj][m][n] = __builtin_amdgcn_mfma_f32_16x16x32_bf16(Bt[n][k], At[m][k], acc[ai][bj][m][n], 0, 0, 0); __builtin_amdgcn_s_setprio(0); } while (0)
; #define PG8_WAIT_V(n) asm volatile("s_waitcnt vmcnt(" #n ")" ::: "memory")
; #define PG8_WAIT_L(n) asm volatile("s_waitcnt lgkmcnt(" #n ")" ::: "memory")
; #define PG8_BAR __builtin_amdgcn_s_barrier()
; #define PG8_SCHED __builtin_amdgcn_sched_barrier(0)
; template <class Epi, class Sched, bool ALIGN_EPI = false, bool SP2 = false>
; __device__ __forceinline__ void gemm_phase(PG8_LAS unsigned char* lds, const Gemm g, const Sched& S, const Epi& E) {
;     ...
;         for (int t = 0; t < nt; t += 2) {
;             const bool last = (t == nt - 2);
;             const char* a1 = cA + (size_t)(t + 1) * kstep;
;             const char* a2 = last ? nA : cA + (size_t)(t + 2) * kstep; const char* b2 = last ? nB : cB + (size_t)(t + 2) * kstep;
;     ...
;             PG8_LDA(At, 1, 1); PG8_STAGE(PG8_SB(1, 0), b3, voffB); PG8_STAGE(PG8_SB(1, 1), b3 + hstep, voffB); PG8_STAGE(PG8_SA(1, 0), a3, voffA);
;             PG8_WAIT_V(8); PG8_WAIT_L(0); PG8_BAR; PG8_MMA(1, 0, At, B0); PG8_MMA(1, 1, At, B1); PG8_BAR; PG8_SCHED;
;     ...
;         if constexpr (ALIGN_EPI) { if (wr == 0) PG8_BAR; }
	s_add_i32 s20, s49, s27
	v_lshl_add_u64 v[144:145], v[144:145], 0, s[34:35]
	s_mov_b32 m0, s20
	ds_read_b128 v[198:201], v149 offset:49152
	ds_read_b128 v[202:205], v149 offset:50176
	ds_read_b128 v[220:223], v149 offset:51200
	ds_read_b128 v[224:227], v149 offset:52224
	ds_read_b128 v[228:231], v149 offset:53248
	ds_read_b128 v[232:235], v149 offset:54272
	ds_read_b128 v[236:239], v149 offset:55296
	ds_read_b128 v[240:243], v149 offset:56320
	global_load_lds_dwordx4 v[144:145], off
	s_add_i32 m0, s20, 0x2000
	s_add_u32 s18, s18, 0x80080
	v_lshl_add_u64 v[144:145], v[206:207], 0, s[34:35]
	s_addc_u32 s19, s19, 0
	s_add_i32 s20, s50, s27
	global_load_lds_dwordx4 v[144:145], off
	v_lshl_add_u64 v[144:145], s[18:19], 0, v[2:3]
	s_mov_b32 m0, s20
	s_nop 0
	global_load_lds_dwordx4 v[144:145], off
	v_lshl_add_u64 v[144:145], s[18:19], 0, v[132:133]
	s_add_i32 m0, s20, 0x2000
	s_nop 0
	global_load_lds_dwordx4 v[144:145], off
	v_lshl_add_u64 v[144:145], v[244:245], 0, s[34:35]
	s_mov_b32 m0, s39
	s_nop 0
	global_load_lds_dwordx4 v[144:145], off
	v_lshl_add_u64 v[144:145], v[246:247], 0, s[34:35]
	s_mov_b32 m0, s40
	s_nop 0
	global_load_lds_dwordx4 v[144:145], off
	s_waitcnt vmcnt(8)
	s_waitcnt lgkmcnt(0)
	s_barrier
	s_setprio 1
	s_waitcnt lgkmcnt(0)
	v_mfma_f32_16x16x32_bf16 v[60:63], v[150:153], v[198:201], v[60:63]
	v_mfma_f32_16x16x32_bf16 v[60:63], v[154:157], v[202:205], v[60:63]
	v_mfma_f32_16x16x32_bf16 v[52:55], v[158:161], v[198:201], v[52:55]
	v_mfma_f32_16x16x32_bf16 v[52:55], v[162:165], v[202:205], v[52:55]
	v_mfma_f32_16x16x32_bf16 v[64:67], v[166:169], v[198:201], v[64:67]
	v_mfma_f32_16x16x32_bf16 v[64:67], v[170:173], v[202:205], v[64:67]
	v_mfma_f32_16x16x32_bf16 v[56:59], v[174:177], v[198:201], v[56:59]
	v_mfma_f32_16x16x32_bf16 v[56:59], v[178:181], v[202:205], v[56:59]
	v_mfma_f32_16x16x32_bf16 v[44:47], v[150:153], v[220:223], v[44:47]
	v_mfma_f32_16x16x32_bf16 v[44:47], v[154:157], v[224:227], v[44:47]
	v_mfma_f32_16x16x32_bf16 v[36:39], v[158:161], v[220:223], v[36:39]
	v_mfma_f32_16x16x32_bf16 v[36:39], v[162:165], v[224:227], v[36:39]
	v_mfma_f32_16x16x32_bf16 v[48:51], v[166:169], v[220:223], v[48:51]
	v_mfma_f32_16x16x32_bf16 v[48:51], v[170:173], v[224:227], v[48:51]
	v_mfma_f32_16x16x32_bf16 v[40:43], v[174:177], v[220:223], v[40:43]
	v_mfma_f32_16x16x32_bf16 v[40:43], v[178:181], v[224:227], v[40:43]
	s_setprio 0
	s_setprio 1
	v_mfma_f32_16x16x32_bf16 v[28:31], v[150:153], v[228:231], v[28:31]
	v_mfma_f32_16x16x32_bf16 v[28:31], v[154:157], v[232:235], v[28:31]
	v_mfma_f32_16x16x32_bf16 v[20:23], v[158:161], v[228:231], v[20:23]
	v_mfma_f32_16x16x32_bf16 v[20:23], v[162:165], v[232:235], v[20:23]
	v_mfma_f32_16x16x32_bf16 v[32:35], v[166:169], v[228:231], v[32:35]
	v_mfma_f32_16x16x32_bf16 v[32:35], v[170:173], v[232:235], v[32:35]
	v_mfma_f32_16x16x32_bf16 v[24:27], v[174:177], v[228:231], v[24:27]
	v_mfma_f32_16x16x32_bf16 v[24:27], v[178:181], v[232:235], v[24:27]
	v_mfma_f32_16x16x32_bf16 v[12:15], v[150:153], v[236:239], v[12:15]
	v_mfma_f32_16x16x32_bf16 v[12:15], v[154:157], v[240:243], v[12:15]
	v_mfma_f32_16x16x32_bf16 v[4:7], v[158:161], v[236:239], v[4:7]
	v_mfma_f32_16x16x32_bf16 v[4:7], v[162:165], v[240:243], v[4:7]
	v_mfma_f32_16x16x32_bf16 v[16:19], v[166:169], v[236:239], v[16:19]
	v_mfma_f32_16x16x32_bf16 v[16:19], v[170:173], v[240:243], v[16:19]
	v_mfma_f32_16x16x32_bf16 v[8:11], v[174:177], v[236:239], v[8:11]
	v_mfma_f32_16x16x32_bf16 v[8:11], v[178:181], v[240:243], v[8:11]
	s_setprio 0
	s_barrier
	s_add_i32 s48, s48, 2
	s_add_u32 s16, s16, 0x100
	s_addc_u32 s17, s17, 0
	s_add_u32 s46, s46, 0x100
	s_addc_u32 s47, s47, 0
	s_cmp_gt_u32 s48, 29
	s_cbranch_scc0 .LBB11_456
	s_and_b64 vcc, exec, s[6:7]
	s_cbranch_vccz .LBB11_459
	s_barrier

; #define PG8_STAGE(bufoff, gbase, voff) do { _Pragma("unroll") for (int _i = 0; _i < 2; ++_i) \
;         __builtin_amdgcn_global_load_lds((const unsigned*)((const char*)(gbase) + (voff)[_i]), (PG8_LAS unsigned*)(lds + (bufoff) + ldsw + _i * 8192), 16, 0, 0); } while (0)
; #define PG8_LDA(dst, b, h) do { _Pragma("unroll") for (int m = 0; m < 4; ++m) _Pragma("unroll") for (int k = 0; k < 2; ++k) dst[m][k] = *(const PG8_LAS bf16x8*)(lds + PG8_SA(b, h) + aoff + m * 2048 + k * 1024); } while (0)
; #define PG8_LDB(dst, b, h) do { _Pragma("unroll") for (int n = 0; n < 2; ++n) _Pragma("unroll") for (int k = 0; k < 2; ++k) dst[n][k] = *(const PG8_LAS bf16x8*)(lds + PG8_SB(b, h) + boff + n * 2048 + k * 1024); } while (0)
; #define PG8_WAIT_V(n) asm volatile("s_waitcnt vmcnt(" #n ")" ::: "memory")
; #define PG8_WAIT_L(n) asm volatile("s_waitcnt lgkmcnt(" #n ")" ::: "memory")
; #define PG8_BAR __builtin_amdgcn_s_barrier()
; #define PG8_SCHED __builtin_amdgcn_sched_barrier(0)
; template <class Epi, class Sched, bool ALIGN_EPI = false, bool SP2 = false>
; __device__ __forceinline__ void gemm_phase(PG8_LAS unsigned char* lds, const Gemm g, const Sched& S, const Epi& E) {
;     ...
;         const char* nA = has_next ? (const char*)g.A + (size_t)nxt.pm * tstep : cA; const char* nB = has_next ? (const char*)g.Bt + (size_t)nxt.pn * tstep : cB;
;         for (int t = 0; t < nt; t += 2) {
;             const bool last = (t == nt - 2);
;             const char* a1 = cA + (size_t)(t + 1) * kstep;
;             const char* a2 = last ? nA : cA + (size_t)(t + 2) * kstep; const char* b2 = last ? nB : cB + (size_t)(t + 2) * kstep;
;             const char* a3 = a2 + kstep; const char* b3 = b2 + kstep;
;             if (last && has_next) S.a_ready(nxt);
;             if constexpr (SP2) {
;             PG8_LDB(B0, 0, 0); PG8_LDB(B1, 0, 1); PG8_SCHED; PG8_LDA(At, 0, 0); PG8_STAGE(PG8_SA(1, 1), a1 + hstep, voffA);
;             PG8_WAIT_V(8); PG8_WAIT_L(0); PG8_BAR; PG8_MMA(0, 0, At, B0); PG8_MMA(0, 1, At, B1); PG8_BAR; PG8_SCHED;
;             PG8_LDA(At, 0, 1); PG8_STAGE(PG8_SB(0, 0), b2, voffB); PG8_STAGE(PG8_SB(0, 1), b2 + hstep, voffB); PG8_STAGE(PG8_SA(0, 0), a2, voffA);
;             PG8_WAIT_V(8); PG8_WAIT_L(0); PG8_BAR; PG8_MMA(1, 0, At, B0); PG8_MMA(1, 1, At, B1); PG8_BAR; PG8_SCHED;
.LBB11_638:
	s_add_u32 s20, s18, 0xfff80080
	s_addc_u32 s21, s19, -1
	s_add_i32 s49, 0, 0x10000
	s_cmp_eq_u32 s48, 28
	s_cselect_b32 s23, s13, s21
	s_cselect_b32 s22, s44, s20
	v_add_u32_e32 v144, s49, v147
	s_cselect_b32 s21, s11, s47
	s_cselect_b32 s20, s45, s46
	s_add_i32 s52, 0, 0x14000
	ds_read_b128 v[150:153], v144
	ds_read_b128 v[154:157], v144 offset:1024
	ds_read_b128 v[158:161], v144 offset:2048
	ds_read_b128 v[162:165], v144 offset:3072
	v_add_u32_e32 v144, s52, v147
	ds_read_b128 v[166:169], v144
	ds_read_b128 v[170:173], v144 offset:1024
	ds_read_b128 v[174:177], v144 offset:2048
	ds_read_b128 v[178:181], v144 offset:3072
	v_lshl_add_u64 v[144:145], s[18:19], 0, v[140:141]
	s_add_i32 m0, s33, 0xc000
	ds_read_b128 v[198:201], v149
	ds_read_b128 v[202:205], v149 offset:1024
	ds_read_b128 v[220:223], v149 offset:2048
	ds_read_b128 v[224:227], v149 offset:3072
	ds_read_b128 v[228:231], v149 offset:4096
	ds_read_b128 v[232:235], v149 offset:5120
	ds_read_b128 v[236:239], v149 offset:6144
	ds_read_b128 v[240:243], v149 offset:7168
	global_load_lds_dwordx4 v[144:145], off
	v_lshl_add_u64 v[144:145], s[18:19], 0, v[142:143]
	s_add_i32 m0, s33, 0xe000
	s_nop 0
	global_load_lds_dwordx4 v[144:145], off
	s_waitcnt vmcnt(8)
	s_waitcnt lgkmcnt(0)
	s_barrier
	s_setprio 1
	s_waitcnt lgkmcnt(0)
	v_mfma_f32_16x16x32_bf16 v[128:131], v[150:153], v[198:201], v[128:131]
	v_mfma_f32_16x16x32_bf16 v[128:131], v[154:157], v[202:205], v[128:131]
	v_mfma_f32_16x16x32_bf16 v[124:127], v[158:161], v[198:201], v[124:127]
	v_mfma_f32_16x16x32_bf16 v[124:127], v[162:165], v[202:205], v[124:127]
	v_mfma_f32_16x16x32_bf16 v[116:119], v[166:169], v[198:201], v[116:119]
	v_mfma_f32_16x16x32_bf16 v[116:119], v[170:173], v[202:205], v[116:119]
	v_mfma_f32_16x16x32_bf16 v[108:111], v[174:177], v[198:201], v[108:111]
	v_mfma_f32_16x16x32_bf16 v[108:111], v[178:181], v[202:205], v[108:111]
	v_mfma_f32_16x16x32_bf16 v[120:123], v[150:153], v[220:223], v[120:123]
	v_mfma_f32_16x16x32_bf16 v[120:123], v[154:157], v[224:227], v[120:123]
	v_mfma_f32_16x16x32_bf16 v[112:115], v[158:161], v[220:223], v[112:115]
	v_mfma_f32_16x16x32_bf16 v[112:115], v[162:165], v[224:227], v[112:115]
	v_mfma_f32_16x16x32_bf16 v[100:103], v[166:169], v[220:223], v[100:103]
	v_mfma_f32_16x16x32_bf16 v[100:103], v[170:173], v[224:227], v[100:103]
	v_mfma_f32_16x16x32_bf16 v[92:95], v[174:177], v[220:223], v[92:95]
	v_mfma_f32_16x16x32_bf16 v[92:95], v[178:181], v[224:227], v[92:95]
	s_setprio 0
	s_setprio 1
	v_mfma_f32_16x16x32_bf16 v[104:107], v[150:153], v[228:231], v[104:107]
	v_mfma_f32_16x16x32_bf16 v[104:107], v[154:157], v[232:235], v[104:107]
	v_mfma_f32_16x16x32_bf16 v[96:99], v[158:161], v[228:231], v[96:99]
	v_mfma_f32_16x16x32_bf16 v[96:99], v[162:165], v[232:235], v[96:99]
	v_mfma_f32_16x16x32_bf16 v[84:87], v[166:169], v[228:231], v[84:87]
	v_mfma_f32_16x16x32_bf16 v[84:87], v[170:173], v[232:235], v[84:87]
	v_mfma_f32_16x16x32_bf16 v[76:79], v[174:177], v[228:231], v[76:79]
	v_mfma_f32_16x16x32_bf16 v[76:79], v[178:181], v[232:235], v[76:79]
	v_mfma_f32_16x16x32_bf16 v[88:91], v[150:153], v[236:239], v[88:91]
	v_mfma_f32_16x16x32_bf16 v[88:91], v[154:157], v[240:243], v[88:91]
	v_mfma_f32_16x16x32_bf16 v[80:83], v[158:161], v[236:239], v[80:83]
	v_mfma_f32_16x16x32_bf16 v[80:83], v[162:165], v[240:243], v[80:83]
	v_mfma_f32_16x16x32_bf16 v[72:75], v[166:169], v[236:239], v[72:75]
	v_mfma_f32_16x16x32_bf16 v[72:75], v[170:173], v[240:243], v[72:75]
	v_mfma_f32_16x16x32_bf16 v[68:71], v[174:177], v[236:239], v[68:71]
	v_mfma_f32_16x16x32_bf16 v[68:71], v[178:181], v[240:243], v[68:71]
	s_setprio 0
	s_barrier
	s_add_i32 s49, s49, s30
	v_lshl_add_u64 v[144:145], s[20:21], 0, v[2:3]
	s_mov_b32 m0, s49
	ds_read_b128 v[198:201], v149 offset:16384
	ds_read_b128 v[202:205], v149 offset:17408
	ds_read_b128 v[220:223], v149 offset:18432
	ds_read_b128 v[224:227], v149 offset:19456
	ds_read_b128 v[228:231], v149 offset:20480
	ds_read_b128 v[232:235], v149 offset:21504
	ds_read_b128 v[236:239], v149 offset:22528
	ds_read_b128 v[240:243], v149 offset:23552
	global_load_lds_dwordx4 v[144:145], off
	s_add_i32 m0, s49, 0x2000
	s_add_u32 s50, s20, 0x80000
	v_lshl_add_u64 v[184:185], s[20:21], 0, v[132:133]
	s_addc_u32 s51, s21, 0
	s_add_i32 s49, s52, s30
	global_load_lds_dwordx4 v[184:185], off
	v_lshl_add_u64 v[186:187], s[50:51], 0, v[2:3]
	s_mov_b32 m0, s49
	v_lshl_add_u64 v[196:197], s[22:23], 0, v[134:135]
	global_load_lds_dwordx4 v[186:187], off
	v_lshl_add_u64 v[186:187], s[50:51], 0, v[132:133]
	s_add_i32 m0, s49, 0x2000
	s_nop 0
	global_load_lds_dwordx4 v[186:187], off
	v_lshl_add_u64 v[186:187], s[22:23], 0, v[136:137]
	s_mov_b32 m0, s33
	s_nop 0
	global_load_lds_dwordx4 v[186:187], off
	s_mov_b32 m0, s36
	s_nop 0
	global_load_lds_dwordx4 v[196:197], off
	s_waitcnt vmcnt(8)
	s_waitcnt lgkmcnt(0)
	s_barrier
; #define PG8_STAGE(bufoff, gbase, voff) do { _Pragma("unroll") for (int _i = 0; _i < 2; ++_i) \
;         __builtin_amdgcn_global_load_lds((const unsigned*)((const char*)(gbase) + (voff)[_i]), (PG8_LAS unsigned*)(lds + (bufoff) + ldsw + _i * 8192), 16, 0, 0); } while (0)
; #define PG8_LDA(dst, b, h) do { _Pragma("unroll") for (int m = 0; m < 4; ++m) _Pragma("unroll") for (int k = 0; k < 2; ++k) dst[m][k] = *(const PG8_LAS bf16x8*)(lds + PG8_SA(b, h) + aoff + m * 2048 + k * 1024); } while (0)
; #define PG8_LDB(dst, b, h) do { _Pragma("unroll") for (int n = 0; n < 2; ++n) _Pragma("unroll") for (int k = 0; k < 2; ++k) dst[n][k] = *(const PG8_LAS bf16x8*)(lds + PG8_SB(b, h) + boff + n * 2048 + k * 1024); } while (0)
; #define PG8_MMA(ai, bj, At, Bt) do { __builtin_amdgcn_s_setprio(1); _Pragma("unroll") for (int m = 0; m < 4; ++m) _Pragma("unroll") for (int n = 0; n < 2; ++n) _Pragma("unroll") for (int k = 0; k < 2; ++k) \
;         acc[ai][bj][m][n] = __builtin_amdgcn_mfma_f32_16x16x32_bf16(Bt[n][k], At[m][k], acc[ai][bj][m][n], 0, 0, 0); __builtin_amdgcn_s_setprio(0); } while (0)
; #define PG8_WAIT_V(n) asm volatile("s_waitcnt vmcnt(" #n ")" ::: "memory")
; #define PG8_WAIT_L(n) asm volatile("s_waitcnt lgkmcnt(" #n ")" ::: "memory")
; #define PG8_BAR __builtin_amdgcn_s_barrier()
; #define PG8_SCHED __builtin_amdgcn_sched_barrier(0)
; template <class Epi, class Sched, bool ALIGN_EPI = false, bool SP2 = false>
; __device__ __forceinline__ void gemm_phase(PG8_LAS unsigned char* lds, const Gemm g, const Sched& S, const Epi& E) {
;     ...
;             PG8_WAIT_V(8); PG8_WAIT_L(0); PG8_BAR; PG8_MMA(1, 0, At, B0); PG8_MMA(1, 1, At, B1); PG8_BAR; PG8_SCHED;
;             PG8_LDB(B0, 1, 0); PG8_LDB(B1, 1, 1); PG8_SCHED; PG8_LDA(At, 1, 0); PG8_STAGE(PG8_SA(0, 1), a2 + hstep, voffA);
;             PG8_WAIT_V(8); PG8_WAIT_L(0); PG8_BAR; PG8_MMA(0, 0, At, B0); PG8_MMA(0, 1, At, B1); PG8_BAR; PG8_SCHED;
;             PG8_LDA(At, 1, 1); PG8_STAGE(PG8_SB(1, 0), b3, voffB); PG8_STAGE(PG8_SB(1, 1), b3 + hstep, voffB); PG8_STAGE(PG8_SA(1, 0), a3, voffA);
	s_setprio 1
	s_waitcnt lgkmcnt(0)
	v_mfma_f32_16x16x32_bf16 v[64:67], v[150:153], v[198:201], v[64:67]
	v_mfma_f32_16x16x32_bf16 v[64:67], v[154:157], v[202:205], v[64:67]
	v_mfma_f32_16x16x32_bf16 v[60:63], v[158:161], v[198:201], v[60:63]
	v_mfma_f32_16x16x32_bf16 v[60:63], v[162:165], v[202:205], v[60:63]
	v_mfma_f32_16x16x32_bf16 v[52:55], v[166:169], v[198:201], v[52:55]
	v_mfma_f32_16x16x32_bf16 v[52:55], v[170:173], v[202:205], v[52:55]
	v_mfma_f32_16x16x32_bf16 v[44:47], v[174:177], v[198:201], v[44:47]
	v_mfma_f32_16x16x32_bf16 v[44:47], v[178:181], v[202:205], v[44:47]
	v_mfma_f32_16x16x32_bf16 v[56:59], v[150:153], v[220:223], v[56:59]
	v_mfma_f32_16x16x32_bf16 v[56:59], v[154:157], v[224:227], v[56:59]
	v_mfma_f32_16x16x32_bf16 v[48:51], v[158:161], v[220:223], v[48:51]
	v_mfma_f32_16x16x32_bf16 v[48:51], v[162:165], v[224:227], v[48:51]
	v_mfma_f32_16x16x32_bf16 v[36:39], v[166:169], v[220:223], v[36:39]
	v_mfma_f32_16x16x32_bf16 v[36:39], v[170:173], v[224:227], v[36:39]
	v_mfma_f32_16x16x32_bf16 v[28:31], v[174:177], v[220:223], v[28:31]
	v_mfma_f32_16x16x32_bf16 v[28:31], v[178:181], v[224:227], v[28:31]
	s_setprio 0
	s_setprio 1
	v_mfma_f32_16x16x32_bf16 v[40:43], v[150:153], v[228:231], v[40:43]
	v_mfma_f32_16x16x32_bf16 v[40:43], v[154:157], v[232:235], v[40:43]
	v_mfma_f32_16x16x32_bf16 v[32:35], v[158:161], v[228:231], v[32:35]
	v_mfma_f32_16x16x32_bf16 v[32:35], v[162:165], v[232:235], v[32:35]
	v_mfma_f32_16x16x32_bf16 v[20:23], v[166:169], v[228:231], v[20:23]
	v_mfma_f32_16x16x32_bf16 v[20:23], v[170:173], v[232:235], v[20:23]
	v_mfma_f32_16x16x32_bf16 v[12:15], v[174:177], v[228:231], v[12:15]
	v_mfma_f32_16x16x32_bf16 v[12:15], v[178:181], v[232:235], v[12:15]
	v_mfma_f32_16x16x32_bf16 v[24:27], v[150:153], v[236:239], v[24:27]
	v_mfma_f32_16x16x32_bf16 v[24:27], v[154:157], v[240:243], v[24:27]
	v_mfma_f32_16x16x32_bf16 v[16:19], v[158:161], v[236:239], v[16:19]
	v_mfma_f32_16x16x32_bf16 v[16:19], v[162:165], v[240:243], v[16:19]
	v_mfma_f32_16x16x32_bf16 v[8:11], v[166:169], v[236:239], v[8:11]
	v_mfma_f32_16x16x32_bf16 v[8:11], v[170:173], v[240:243], v[8:11]
	v_mfma_f32_16x16x32_bf16 v[4:7], v[174:177], v[236:239], v[4:7]
	v_mfma_f32_16x16x32_bf16 v[4:7], v[178:181], v[240:243], v[4:7]
	s_setprio 0
	s_barrier
	s_add_i32 s49, 0, 0x18000
	s_add_i32 s50, 0, 0x1c000
	v_add_u32_e32 v162, s49, v147
	v_add_u32_e32 v178, s50, v147
	ds_read_b128 v[150:153], v162
	ds_read_b128 v[154:157], v162 offset:1024
	ds_read_b128 v[158:161], v162 offset:2048
	ds_read_b128 v[162:165], v162 offset:3072
	ds_read_b128 v[166:169], v178
	ds_read_b128 v[170:173], v178 offset:1024
	ds_read_b128 v[174:177], v178 offset:2048
	ds_read_b128 v[178:181], v178 offset:3072
	s_add_u32 s22, s22, 0x80000
	s_addc_u32 s23, s23, 0
	s_mov_b32 m0, s37
	v_lshl_add_u64 v[206:207], s[22:23], 0, v[136:137]
	ds_read_b128 v[198:201], v149 offset:32768
	ds_read_b128 v[202:205], v149 offset:33792
	ds_read_b128 v[220:223], v149 offset:34816
	ds_read_b128 v[224:227], v149 offset:35840
	ds_read_b128 v[228:231], v149 offset:36864
	ds_read_b128 v[232:235], v149 offset:37888
	ds_read_b128 v[236:239], v149 offset:38912
	ds_read_b128 v[240:243], v149 offset:39936
	global_load_lds_dwordx4 v[206:207], off
	v_lshl_add_u64 v[206:207], s[22:23], 0, v[134:135]
	s_mov_b32 m0, s38
	s_nop 0
	global_load_lds_dwordx4 v[206:207], off
	s_waitcnt vmcnt(8)
	s_waitcnt lgkmcnt(0)
	s_barrier
	s_setprio 1
	s_waitcnt lgkmcnt(0)
	v_mfma_f32_16x16x32_bf16 v[128:131], v[150:153], v[198:201], v[128:131]
	v_mfma_f32_16x16x32_bf16 v[128:131], v[154:157], v[202:205], v[128:131]
	v_mfma_f32_16x16x32_bf16 v[124:127], v[158:161], v[198:201], v[124:127]
	v_mfma_f32_16x16x32_bf16 v[124:127], v[162:165], v[202:205], v[124:127]
	v_mfma_f32_16x16x32_bf16 v[116:119], v[166:169], v[198:201], v[116:119]
	v_mfma_f32_16x16x32_bf16 v[116:119], v[170:173], v[202:205], v[116:119]
	v_mfma_f32_16x16x32_bf16 v[108:111], v[174:177], v[198:201], v[108:111]
	v_mfma_f32_16x16x32_bf16 v[108:111], v[178:181], v[202:205], v[108:111]
	v_mfma_f32_16x16x32_bf16 v[120:123], v[150:153], v[220:223], v[120:123]
	v_mfma_f32_16x16x32_bf16 v[120:123], v[154:157], v[224:227], v[120:123]
	v_mfma_f32_16x16x32_bf16 v[112:115], v[158:161], v[220:223], v[112:115]
	v_mfma_f32_16x16x32_bf16 v[112:115], v[162:165], v[224:227], v[112:115]
	v_mfma_f32_16x16x32_bf16 v[100:103], v[166:169], v[220:223], v[100:103]
	v_mfma_f32_16x16x32_bf16 v[100:103], v[170:173], v[224:227], v[100:103]
	v_mfma_f32_16x16x32_bf16 v[92:95], v[174:177], v[220:223], v[92:95]
	v_mfma_f32_16x16x32_bf16 v[92:95], v[178:181], v[224:227], v[92:95]
	s_setprio 0
	s_setprio 1
	v_mfma_f32_16x16x32_bf16 v[104:107], v[150:153], v[228:231], v[104:107]
	v_mfma_f32_16x16x32_bf16 v[104:107], v[154:157], v[232:235], v[104:107]
	v_mfma_f32_16x16x32_bf16 v[96:99], v[158:161], v[228:231], v[96:99]
	v_mfma_f32_16x16x32_bf16 v[96:99], v[162:165], v[232:235], v[96:99]
	v_mfma_f32_16x16x32_bf16 v[84:87], v[166:169], v[228:231], v[84:87]
	v_mfma_f32_16x16x32_bf16 v[84:87], v[170:173], v[232:235], v[84:87]
	v_mfma_f32_16x16x32_bf16 v[76:79], v[174:177], v[228:231], v[76:79]
	v_mfma_f32_16x16x32_bf16 v[76:79], v[178:181], v[232:235], v[76:79]
	v_mfma_f32_16x16x32_bf16 v[88:91], v[150:153], v[236:239], v[88:91]
	v_mfma_f32_16x16x32_bf16 v[88:91], v[154:157], v[240:243], v[88:91]
	v_mfma_f32_16x16x32_bf16 v[80:83], v[158:161], v[236:239], v[80:83]
	v_mfma_f32_16x16x32_bf16 v[80:83], v[162:165], v[240:243], v[80:83]
	v_mfma_f32_16x16x32_bf16 v[72:75], v[166:169], v[236:239], v[72:75]
	v_mfma_f32_16x16x32_bf16 v[72:75], v[170:173], v[240:243], v[72:75]
	v_mfma_f32_16x16x32_bf16 v[68:71], v[174:177], v[236:239], v[68:71]
	v_mfma_f32_16x16x32_bf16 v[68:71], v[178:181], v[240:243], v[68:71]
	s_setprio 0
	s_barrier
; #define PG8_STAGE(bufoff, gbase, voff) do { _Pragma("unroll") for (int _i = 0; _i < 2; ++_i) \
;         __builtin_amdgcn_global_load_lds((const unsigned*)((const char*)(gbase) + (voff)[_i]), (PG8_LAS unsigned*)(lds + (bufoff) + ldsw + _i * 8192), 16, 0, 0); } while (0)
; #define PG8_LDA(dst, b, h) do { _Pragma("unroll") for (int m = 0; m < 4; ++m) _Pragma("unroll") for (int k = 0; k < 2; ++k) dst[m][k] = *(const PG8_LAS bf16x8*)(lds + PG8_SA(b, h) + aoff + m * 2048 + k * 1024); } while (0)
; #define PG8_MMA(ai, bj, At, Bt) do { __builtin_amdgcn_s_setprio(1); _Pragma("unroll") for (int m = 0; m < 4; ++m) _Pragma("unroll") for (int n = 0; n < 2; ++n) _Pragma("unroll") for (int k = 0; k < 2; ++k) \
;         acc[ai][bj][m][n] = __builtin_amdgcn_mfma_f32_16x16x32_bf16(Bt[n][k], At[m][k], acc[ai][bj][m][n], 0, 0, 0); __builtin_amdgcn_s_setprio(0); } while (0)
; #define PG8_WAIT_V(n) asm volatile("s_waitcnt vmcnt(" #n ")" ::: "memory")
; #define PG8_WAIT_L(n) asm volatile("s_waitcnt lgkmcnt(" #n ")" ::: "memory")
; #define PG8_BAR __builtin_amdgcn_s_barrier()
; #define PG8_SCHED __builtin_amdgcn_sched_barrier(0)
; template <class Epi, class Sched, bool ALIGN_EPI = false, bool SP2 = false>
; __device__ __forceinline__ void gemm_phase(PG8_LAS unsigned char* lds, const Gemm g, const Sched& S, const Epi& E) {
;     ...
;         for (int t = 0; t < nt; t += 2) {
;             const bool last = (t == nt - 2);
;             const char* a1 = cA + (size_t)(t + 1) * kstep;
;             const char* a2 = last ? nA : cA + (size_t)(t + 2) * kstep; const char* b2 = last ? nB : cB + (size_t)(t + 2) * kstep;
;     ...
;             PG8_LDA(At, 1, 1); PG8_STAGE(PG8_SB(1, 0), b3, voffB); PG8_STAGE(PG8_SB(1, 1), b3 + hstep, voffB); PG8_STAGE(PG8_SA(1, 0), a3, voffA);
;             PG8_WAIT_V(8); PG8_WAIT_L(0); PG8_BAR; PG8_MMA(1, 0, At, B0); PG8_MMA(1, 1, At, B1); PG8_BAR; PG8_SCHED;
;     ...
;         if constexpr (ALIGN_EPI) { if (wr == 0) PG8_BAR; }
	s_add_i32 s22, s49, s30
	v_lshl_add_u64 v[144:145], v[144:145], 0, s[34:35]
	s_mov_b32 m0, s22
	ds_read_b128 v[198:201], v149 offset:49152
	ds_read_b128 v[202:205], v149 offset:50176
	ds_read_b128 v[220:223], v149 offset:51200
	ds_read_b128 v[224:227], v149 offset:52224
	ds_read_b128 v[228:231], v149 offset:53248
	ds_read_b128 v[232:235], v149 offset:54272
	ds_read_b128 v[236:239], v149 offset:55296
	ds_read_b128 v[240:243], v149 offset:56320
	global_load_lds_dwordx4 v[144:145], off
	s_add_i32 m0, s22, 0x2000
	s_add_u32 s20, s20, 0x80080
	v_lshl_add_u64 v[144:145], v[184:185], 0, s[34:35]
	s_addc_u32 s21, s21, 0
	s_add_i32 s22, s50, s30
	global_load_lds_dwordx4 v[144:145], off
	v_lshl_add_u64 v[144:145], s[20:21], 0, v[2:3]
	s_mov_b32 m0, s22
	s_nop 0
	global_load_lds_dwordx4 v[144:145], off
	v_lshl_add_u64 v[144:145], s[20:21], 0, v[132:133]
	s_add_i32 m0, s22, 0x2000
	s_nop 0
	global_load_lds_dwordx4 v[144:145], off
	v_lshl_add_u64 v[144:145], v[186:187], 0, s[34:35]
	s_mov_b32 m0, s39
	s_nop 0
	global_load_lds_dwordx4 v[144:145], off
	v_lshl_add_u64 v[144:145], v[196:197], 0, s[34:35]
	s_mov_b32 m0, s40
	s_nop 0
	global_load_lds_dwordx4 v[144:145], off
	s_waitcnt vmcnt(8)
	s_waitcnt lgkmcnt(0)
	s_barrier
	s_setprio 1
	s_waitcnt lgkmcnt(0)
	v_mfma_f32_16x16x32_bf16 v[64:67], v[150:153], v[198:201], v[64:67]
	v_mfma_f32_16x16x32_bf16 v[64:67], v[154:157], v[202:205], v[64:67]
	v_mfma_f32_16x16x32_bf16 v[60:63], v[158:161], v[198:201], v[60:63]
	v_mfma_f32_16x16x32_bf16 v[60:63], v[162:165], v[202:205], v[60:63]
	v_mfma_f32_16x16x32_bf16 v[52:55], v[166:169], v[198:201], v[52:55]
	v_mfma_f32_16x16x32_bf16 v[52:55], v[170:173], v[202:205], v[52:55]
	v_mfma_f32_16x16x32_bf16 v[44:47], v[174:177], v[198:201], v[44:47]
	v_mfma_f32_16x16x32_bf16 v[44:47], v[178:181], v[202:205], v[44:47]
	v_mfma_f32_16x16x32_bf16 v[56:59], v[150:153], v[220:223], v[56:59]
	v_mfma_f32_16x16x32_bf16 v[56:59], v[154:157], v[224:227], v[56:59]
	v_mfma_f32_16x16x32_bf16 v[48:51], v[158:161], v[220:223], v[48:51]
	v_mfma_f32_16x16x32_bf16 v[48:51], v[162:165], v[224:227], v[48:51]
	v_mfma_f32_16x16x32_bf16 v[36:39], v[166:169], v[220:223], v[36:39]
	v_mfma_f32_16x16x32_bf16 v[36:39], v[170:173], v[224:227], v[36:39]
	v_mfma_f32_16x16x32_bf16 v[28:31], v[174:177], v[220:223], v[28:31]
	v_mfma_f32_16x16x32_bf16 v[28:31], v[178:181], v[224:227], v[28:31]
	s_setprio 0
	s_setprio 1
	v_mfma_f32_16x16x32_bf16 v[40:43], v[150:153], v[228:231], v[40:43]
	v_mfma_f32_16x16x32_bf16 v[40:43], v[154:157], v[232:235], v[40:43]
	v_mfma_f32_16x16x32_bf16 v[32:35], v[158:161], v[228:231], v[32:35]
	v_mfma_f32_16x16x32_bf16 v[32:35], v[162:165], v[232:235], v[32:35]
	v_mfma_f32_16x16x32_bf16 v[20:23], v[166:169], v[228:231], v[20:23]
	v_mfma_f32_16x16x32_bf16 v[20:23], v[170:173], v[232:235], v[20:23]
	v_mfma_f32_16x16x32_bf16 v[12:15], v[174:177], v[228:231], v[12:15]
	v_mfma_f32_16x16x32_bf16 v[12:15], v[178:181], v[232:235], v[12:15]
	v_mfma_f32_16x16x32_bf16 v[24:27], v[150:153], v[236:239], v[24:27]
	v_mfma_f32_16x16x32_bf16 v[24:27], v[154:157], v[240:243], v[24:27]
	v_mfma_f32_16x16x32_bf16 v[16:19], v[158:161], v[236:239], v[16:19]
	v_mfma_f32_16x16x32_bf16 v[16:19], v[162:165], v[240:243], v[16:19]
	v_mfma_f32_16x16x32_bf16 v[8:11], v[166:169], v[236:239], v[8:11]
	v_mfma_f32_16x16x32_bf16 v[8:11], v[170:173], v[240:243], v[8:11]
	v_mfma_f32_16x16x32_bf16 v[4:7], v[174:177], v[236:239], v[4:7]
	v_mfma_f32_16x16x32_bf16 v[4:7], v[178:181], v[240:243], v[4:7]
	s_setprio 0
	s_barrier
	s_add_i32 s48, s48, 2
	s_add_u32 s18, s18, 0x100
	s_addc_u32 s19, s19, 0
	s_add_u32 s46, s46, 0x100
	s_addc_u32 s47, s47, 0
	s_cmp_gt_u32 s48, 29
	s_cbranch_scc0 .LBB11_638
	s_and_b64 vcc, exec, s[4:5]
	s_cbranch_vccz .LBB11_641
	s_barrier

; #define PG8_STAGE(bufoff, gbase, voff) do { _Pragma("unroll") for (int _i = 0; _i < 2; ++_i) \
;         __builtin_amdgcn_global_load_lds((const unsigned*)((const char*)(gbase) + (voff)[_i]), (PG8_LAS unsigned*)(lds + (bufoff) + ldsw + _i * 8192), 16, 0, 0); } while (0)
; #define PG8_LDA(dst, b, h) do { _Pragma("unroll") for (int m = 0; m < 4; ++m) _Pragma("unroll") for (int k = 0; k < 2; ++k) dst[m][k] = *(const PG8_LAS bf16x8*)(lds + PG8_SA(b, h) + aoff + m * 2048 + k * 1024); } while (0)
; #define PG8_LDB(dst, b, h) do { _Pragma("unroll") for (int n = 0; n < 2; ++n) _Pragma("unroll") for (int k = 0; k < 2; ++k) dst[n][k] = *(const PG8_LAS bf16x8*)(lds + PG8_SB(b, h) + boff + n * 2048 + k * 1024); } while (0)
; #define PG8_WAIT_V(n) asm volatile("s_waitcnt vmcnt(" #n ")" ::: "memory")
; #define PG8_WAIT_L(n) asm volatile("s_waitcnt lgkmcnt(" #n ")" ::: "memory")
; #define PG8_BAR __builtin_amdgcn_s_barrier()
; #define PG8_SCHED __builtin_amdgcn_sched_barrier(0)
; template <class Epi, class Sched, bool ALIGN_EPI = false, bool SP2 = false>
; __device__ __forceinline__ void gemm_phase(PG8_LAS unsigned char* lds, const Gemm g, const Sched& S, const Epi& E) {
;     ...
;         const char* nA = has_next ? (const char*)g.A + (size_t)nxt.pm * tstep : cA; const char* nB = has_next ? (const char*)g.Bt + (size_t)nxt.pn * tstep : cB;
;         for (int t = 0; t < nt; t += 2) {
;             const bool last = (t == nt - 2);
;             const char* a1 = cA + (size_t)(t + 1) * kstep;
;             const char* a2 = last ? nA : cA + (size_t)(t + 2) * kstep; const char* b2 = last ? nB : cB + (size_t)(t + 2) * kstep;
;             const char* a3 = a2 + kstep; const char* b3 = b2 + kstep;
;             if (last && has_next) S.a_ready(nxt);
;             if constexpr (SP2) {
;             PG8_LDB(B0, 0, 0); PG8_LDB(B1, 0, 1); PG8_SCHED; PG8_LDA(At, 0, 0); PG8_STAGE(PG8_SA(1, 1), a1 + hstep, voffA);
;             PG8_WAIT_V(8); PG8_WAIT_L(0); PG8_BAR; PG8_MMA(0, 0, At, B0); PG8_MMA(0, 1, At, B1); PG8_BAR; PG8_SCHED;
;             PG8_LDA(At, 0, 1); PG8_STAGE(PG8_SB(0, 0), b2, voffB); PG8_STAGE(PG8_SB(0, 1), b2 + hstep, voffB); PG8_STAGE(PG8_SA(0, 0), a2, voffA);
;             PG8_WAIT_V(8); PG8_WAIT_L(0); PG8_BAR; PG8_MMA(1, 0, At, B0); PG8_MMA(1, 1, At, B1); PG8_BAR; PG8_SCHED;
.LBB11_913:
	s_add_u32 s16, s14, 0xfff80080
	s_addc_u32 s17, s15, -1
	s_add_i32 s44, 0, 0x10000
	s_cmp_eq_u32 s43, 28
	s_cselect_b32 s19, s9, s17
	s_cselect_b32 s18, s37, s16
	v_add_u32_e32 v144, s44, v146
	s_cselect_b32 s17, s7, s42
	s_cselect_b32 s16, s40, s41
	s_add_i32 s46, 0, 0x14000
	ds_read_b128 v[150:153], v144
	ds_read_b128 v[154:157], v144 offset:1024
	ds_read_b128 v[158:161], v144 offset:2048
	ds_read_b128 v[162:165], v144 offset:3072
	v_add_u32_e32 v144, s46, v146
	ds_read_b128 v[166:169], v144
	ds_read_b128 v[170:173], v144 offset:1024
	ds_read_b128 v[174:177], v144 offset:2048
	ds_read_b128 v[178:181], v144 offset:3072
	v_lshl_add_u64 v[144:145], s[14:15], 0, v[140:141]
	s_add_i32 m0, s24, 0xc000
	ds_read_b128 v[198:201], v148
	ds_read_b128 v[202:205], v148 offset:1024
	ds_read_b128 v[220:223], v148 offset:2048
	ds_read_b128 v[224:227], v148 offset:3072
	ds_read_b128 v[228:231], v148 offset:4096
	ds_read_b128 v[232:235], v148 offset:5120
	ds_read_b128 v[236:239], v148 offset:6144
	ds_read_b128 v[240:243], v148 offset:7168
	global_load_lds_dwordx4 v[144:145], off
	v_lshl_add_u64 v[144:145], s[14:15], 0, v[142:143]
	s_add_i32 m0, s24, 0xe000
	s_nop 0
	global_load_lds_dwordx4 v[144:145], off
	s_waitcnt vmcnt(8)
	s_waitcnt lgkmcnt(0)
	s_barrier
	s_setprio 1
	s_waitcnt lgkmcnt(0)
	v_mfma_f32_16x16x32_bf16 v[128:131], v[150:153], v[198:201], v[128:131]
	v_mfma_f32_16x16x32_bf16 v[128:131], v[154:157], v[202:205], v[128:131]
	v_mfma_f32_16x16x32_bf16 v[124:127], v[158:161], v[198:201], v[124:127]
	v_mfma_f32_16x16x32_bf16 v[124:127], v[162:165], v[202:205], v[124:127]
	v_mfma_f32_16x16x32_bf16 v[116:119], v[166:169], v[198:201], v[116:119]
	v_mfma_f32_16x16x32_bf16 v[116:119], v[170:173], v[202:205], v[116:119]
	v_mfma_f32_16x16x32_bf16 v[108:111], v[174:177], v[198:201], v[108:111]
	v_mfma_f32_16x16x32_bf16 v[108:111], v[178:181], v[202:205], v[108:111]
	v_mfma_f32_16x16x32_bf16 v[120:123], v[150:153], v[220:223], v[120:123]
	v_mfma_f32_16x16x32_bf16 v[120:123], v[154:157], v[224:227], v[120:123]
	v_mfma_f32_16x16x32_bf16 v[112:115], v[158:161], v[220:223], v[112:115]
	v_mfma_f32_16x16x32_bf16 v[112:115], v[162:165], v[224:227], v[112:115]
	v_mfma_f32_16x16x32_bf16 v[100:103], v[166:169], v[220:223], v[100:103]
	v_mfma_f32_16x16x32_bf16 v[100:103], v[170:173], v[224:227], v[100:103]
	v_mfma_f32_16x16x32_bf16 v[92:95], v[174:177], v[220:223], v[92:95]
	v_mfma_f32_16x16x32_bf16 v[92:95], v[178:181], v[224:227], v[92:95]
	s_setprio 0
	s_setprio 1
	v_mfma_f32_16x16x32_bf16 v[104:107], v[150:153], v[228:231], v[104:107]
	v_mfma_f32_16x16x32_bf16 v[104:107], v[154:157], v[232:235], v[104:107]
	v_mfma_f32_16x16x32_bf16 v[96:99], v[158:161], v[228:231], v[96:99]
	v_mfma_f32_16x16x32_bf16 v[96:99], v[162:165], v[232:235], v[96:99]
	v_mfma_f32_16x16x32_bf16 v[84:87], v[166:169], v[228:231], v[84:87]
	v_mfma_f32_16x16x32_bf16 v[84:87], v[170:173], v[232:235], v[84:87]
	v_mfma_f32_16x16x32_bf16 v[76:79], v[174:177], v[228:231], v[76:79]
	v_mfma_f32_16x16x32_bf16 v[76:79], v[178:181], v[232:235], v[76:79]
	v_mfma_f32_16x16x32_bf16 v[88:91], v[150:153], v[236:239], v[88:91]
	v_mfma_f32_16x16x32_bf16 v[88:91], v[154:157], v[240:243], v[88:91]
	v_mfma_f32_16x16x32_bf16 v[80:83], v[158:161], v[236:239], v[80:83]
	v_mfma_f32_16x16x32_bf16 v[80:83], v[162:165], v[240:243], v[80:83]
	v_mfma_f32_16x16x32_bf16 v[72:75], v[166:169], v[236:239], v[72:75]
	v_mfma_f32_16x16x32_bf16 v[72:75], v[170:173], v[240:243], v[72:75]
	v_mfma_f32_16x16x32_bf16 v[68:71], v[174:177], v[236:239], v[68:71]
	v_mfma_f32_16x16x32_bf16 v[68:71], v[178:181], v[240:243], v[68:71]
	s_setprio 0
	s_barrier
	s_add_i32 s44, s44, s23
	v_lshl_add_u64 v[144:145], s[16:17], 0, v[2:3]
	s_mov_b32 m0, s44
	ds_read_b128 v[198:201], v148 offset:16384
	ds_read_b128 v[202:205], v148 offset:17408
	ds_read_b128 v[220:223], v148 offset:18432
	ds_read_b128 v[224:227], v148 offset:19456
	ds_read_b128 v[228:231], v148 offset:20480
	ds_read_b128 v[232:235], v148 offset:21504
	ds_read_b128 v[236:239], v148 offset:22528
	ds_read_b128 v[240:243], v148 offset:23552
	global_load_lds_dwordx4 v[144:145], off
	s_add_i32 m0, s44, 0x2000
	s_add_u32 s44, s16, 0x80000
	v_lshl_add_u64 v[184:185], s[16:17], 0, v[132:133]
	s_addc_u32 s45, s17, 0
	s_add_i32 s46, s46, s23
	global_load_lds_dwordx4 v[184:185], off
	v_lshl_add_u64 v[186:187], s[44:45], 0, v[2:3]
	s_mov_b32 m0, s46
	v_lshl_add_u64 v[196:197], s[18:19], 0, v[134:135]
	global_load_lds_dwordx4 v[186:187], off
	v_lshl_add_u64 v[186:187], s[44:45], 0, v[132:133]
	s_add_i32 m0, s46, 0x2000
	s_nop 0
	global_load_lds_dwordx4 v[186:187], off
	v_lshl_add_u64 v[186:187], s[18:19], 0, v[136:137]
	s_mov_b32 m0, s24
	s_nop 0
	global_load_lds_dwordx4 v[186:187], off
	s_mov_b32 m0, s25
	s_nop 0
	global_load_lds_dwordx4 v[196:197], off
	s_waitcnt vmcnt(8)
	s_waitcnt lgkmcnt(0)
	s_barrier
; #define PG8_STAGE(bufoff, gbase, voff) do { _Pragma("unroll") for (int _i = 0; _i < 2; ++_i) \
;         __builtin_amdgcn_global_load_lds((const unsigned*)((const char*)(gbase) + (voff)[_i]), (PG8_LAS unsigned*)(lds + (bufoff) + ldsw + _i * 8192), 16, 0, 0); } while (0)
; #define PG8_LDA(dst, b, h) do { _Pragma("unroll") for (int m = 0; m < 4; ++m) _Pragma("unroll") for (int k = 0; k < 2; ++k) dst[m][k] = *(const PG8_LAS bf16x8*)(lds + PG8_SA(b, h) + aoff + m * 2048 + k * 1024); } while (0)
; #define PG8_LDB(dst, b, h) do { _Pragma("unroll") for (int n = 0; n < 2; ++n) _Pragma("unroll") for (int k = 0; k < 2; ++k) dst[n][k] = *(const PG8_LAS bf16x8*)(lds + PG8_SB(b, h) + boff + n * 2048 + k * 1024); } while (0)
; #define PG8_MMA(ai, bj, At, Bt) do { __builtin_amdgcn_s_setprio(1); _Pragma("unroll") for (int m = 0; m < 4; ++m) _Pragma("unroll") for (int n = 0; n < 2; ++n) _Pragma("unroll") for (int k = 0; k < 2; ++k) \
;         acc[ai][bj][m][n] = __builtin_amdgcn_mfma_f32_16x16x32_bf16(Bt[n][k], At[m][k], acc[ai][bj][m][n], 0, 0, 0); __builtin_amdgcn_s_setprio(0); } while (0)
; #define PG8_WAIT_V(n) asm volatile("s_waitcnt vmcnt(" #n ")" ::: "memory")
; #define PG8_WAIT_L(n) asm volatile("s_waitcnt lgkmcnt(" #n ")" ::: "memory")
; #define PG8_BAR __builtin_amdgcn_s_barrier()
; #define PG8_SCHED __builtin_amdgcn_sched_barrier(0)
; template <class Epi, class Sched, bool ALIGN_EPI = false, bool SP2 = false>
; __device__ __forceinline__ void gemm_phase(PG8_LAS unsigned char* lds, const Gemm g, const Sched& S, const Epi& E) {
;     ...
;             PG8_WAIT_V(8); PG8_WAIT_L(0); PG8_BAR; PG8_MMA(1, 0, At, B0); PG8_MMA(1, 1, At, B1); PG8_BAR; PG8_SCHED;
;             PG8_LDB(B0, 1, 0); PG8_LDB(B1, 1, 1); PG8_SCHED; PG8_LDA(At, 1, 0); PG8_STAGE(PG8_SA(0, 1), a2 + hstep, voffA);
;             PG8_WAIT_V(8); PG8_WAIT_L(0); PG8_BAR; PG8_MMA(0, 0, At, B0); PG8_MMA(0, 1, At, B1); PG8_BAR; PG8_SCHED;
;             PG8_LDA(At, 1, 1); PG8_STAGE(PG8_SB(1, 0), b3, voffB); PG8_STAGE(PG8_SB(1, 1), b3 + hstep, voffB); PG8_STAGE(PG8_SA(1, 0), a3, voffA);
	s_setprio 1
	s_waitcnt lgkmcnt(0)
	v_mfma_f32_16x16x32_bf16 v[64:67], v[150:153], v[198:201], v[64:67]
	v_mfma_f32_16x16x32_bf16 v[64:67], v[154:157], v[202:205], v[64:67]
	v_mfma_f32_16x16x32_bf16 v[60:63], v[158:161], v[198:201], v[60:63]
	v_mfma_f32_16x16x32_bf16 v[60:63], v[162:165], v[202:205], v[60:63]
	v_mfma_f32_16x16x32_bf16 v[52:55], v[166:169], v[198:201], v[52:55]
	v_mfma_f32_16x16x32_bf16 v[52:55], v[170:173], v[202:205], v[52:55]
	v_mfma_f32_16x16x32_bf16 v[44:47], v[174:177], v[198:201], v[44:47]
	v_mfma_f32_16x16x32_bf16 v[44:47], v[178:181], v[202:205], v[44:47]
	v_mfma_f32_16x16x32_bf16 v[56:59], v[150:153], v[220:223], v[56:59]
	v_mfma_f32_16x16x32_bf16 v[56:59], v[154:157], v[224:227], v[56:59]
	v_mfma_f32_16x16x32_bf16 v[48:51], v[158:161], v[220:223], v[48:51]
	v_mfma_f32_16x16x32_bf16 v[48:51], v[162:165], v[224:227], v[48:51]
	v_mfma_f32_16x16x32_bf16 v[36:39], v[166:169], v[220:223], v[36:39]
	v_mfma_f32_16x16x32_bf16 v[36:39], v[170:173], v[224:227], v[36:39]
	v_mfma_f32_16x16x32_bf16 v[28:31], v[174:177], v[220:223], v[28:31]
	v_mfma_f32_16x16x32_bf16 v[28:31], v[178:181], v[224:227], v[28:31]
	s_setprio 0
	s_setprio 1
	v_mfma_f32_16x16x32_bf16 v[40:43], v[150:153], v[228:231], v[40:43]
	v_mfma_f32_16x16x32_bf16 v[40:43], v[154:157], v[232:235], v[40:43]
	v_mfma_f32_16x16x32_bf16 v[32:35], v[158:161], v[228:231], v[32:35]
	v_mfma_f32_16x16x32_bf16 v[32:35], v[162:165], v[232:235], v[32:35]
	v_mfma_f32_16x16x32_bf16 v[20:23], v[166:169], v[228:231], v[20:23]
	v_mfma_f32_16x16x32_bf16 v[20:23], v[170:173], v[232:235], v[20:23]
	v_mfma_f32_16x16x32_bf16 v[12:15], v[174:177], v[228:231], v[12:15]
	v_mfma_f32_16x16x32_bf16 v[12:15], v[178:181], v[232:235], v[12:15]
	v_mfma_f32_16x16x32_bf16 v[24:27], v[150:153], v[236:239], v[24:27]
	v_mfma_f32_16x16x32_bf16 v[24:27], v[154:157], v[240:243], v[24:27]
	v_mfma_f32_16x16x32_bf16 v[16:19], v[158:161], v[236:239], v[16:19]
	v_mfma_f32_16x16x32_bf16 v[16:19], v[162:165], v[240:243], v[16:19]
	v_mfma_f32_16x16x32_bf16 v[8:11], v[166:169], v[236:239], v[8:11]
	v_mfma_f32_16x16x32_bf16 v[8:11], v[170:173], v[240:243], v[8:11]
	v_mfma_f32_16x16x32_bf16 v[4:7], v[174:177], v[236:239], v[4:7]
	v_mfma_f32_16x16x32_bf16 v[4:7], v[178:181], v[240:243], v[4:7]
	s_setprio 0
	s_barrier
	s_add_i32 s44, 0, 0x18000
	v_add_u32_e32 v149, s44, v146
	s_add_i32 s45, 0, 0x1c000
	ds_read_b128 v[150:153], v149
	ds_read_b128 v[154:157], v149 offset:1024
	ds_read_b128 v[158:161], v149 offset:2048
	ds_read_b128 v[162:165], v149 offset:3072
	v_add_u32_e32 v149, s45, v146
	ds_read_b128 v[166:169], v149
	ds_read_b128 v[170:173], v149 offset:1024
	ds_read_b128 v[174:177], v149 offset:2048
	ds_read_b128 v[178:181], v149 offset:3072
	s_add_u32 s18, s18, 0x80000
	s_addc_u32 s19, s19, 0
	s_mov_b32 m0, s26
	v_lshl_add_u64 v[206:207], s[18:19], 0, v[136:137]
	ds_read_b128 v[198:201], v148 offset:32768
	ds_read_b128 v[202:205], v148 offset:33792
	ds_read_b128 v[220:223], v148 offset:34816
	ds_read_b128 v[224:227], v148 offset:35840
	ds_read_b128 v[228:231], v148 offset:36864
	ds_read_b128 v[232:235], v148 offset:37888
	ds_read_b128 v[236:239], v148 offset:38912
	ds_read_b128 v[240:243], v148 offset:39936
	global_load_lds_dwordx4 v[206:207], off
	v_lshl_add_u64 v[206:207], s[18:19], 0, v[134:135]
	s_mov_b32 m0, s27
	s_nop 0
	global_load_lds_dwordx4 v[206:207], off
	s_waitcnt vmcnt(8)
	s_waitcnt lgkmcnt(0)
	s_barrier
	s_setprio 1
	s_waitcnt lgkmcnt(0)
	v_mfma_f32_16x16x32_bf16 v[128:131], v[150:153], v[198:201], v[128:131]
	v_mfma_f32_16x16x32_bf16 v[128:131], v[154:157], v[202:205], v[128:131]
	v_mfma_f32_16x16x32_bf16 v[124:127], v[158:161], v[198:201], v[124:127]
	v_mfma_f32_16x16x32_bf16 v[124:127], v[162:165], v[202:205], v[124:127]
	v_mfma_f32_16x16x32_bf16 v[116:119], v[166:169], v[198:201], v[116:119]
	v_mfma_f32_16x16x32_bf16 v[116:119], v[170:173], v[202:205], v[116:119]
	v_mfma_f32_16x16x32_bf16 v[108:111], v[174:177], v[198:201], v[108:111]
	v_mfma_f32_16x16x32_bf16 v[108:111], v[178:181], v[202:205], v[108:111]
	v_mfma_f32_16x16x32_bf16 v[120:123], v[150:153], v[220:223], v[120:123]
	v_mfma_f32_16x16x32_bf16 v[120:123], v[154:157], v[224:227], v[120:123]
	v_mfma_f32_16x16x32_bf16 v[112:115], v[158:161], v[220:223], v[112:115]
	v_mfma_f32_16x16x32_bf16 v[112:115], v[162:165], v[224:227], v[112:115]
	v_mfma_f32_16x16x32_bf16 v[100:103], v[166:169], v[220:223], v[100:103]
	v_mfma_f32_16x16x32_bf16 v[100:103], v[170:173], v[224:227], v[100:103]
	v_mfma_f32_16x16x32_bf16 v[92:95], v[174:177], v[220:223], v[92:95]
	v_mfma_f32_16x16x32_bf16 v[92:95], v[178:181], v[224:227], v[92:95]
	s_setprio 0
	s_setprio 1
	v_mfma_f32_16x16x32_bf16 v[104:107], v[150:153], v[228:231], v[104:107]
	v_mfma_f32_16x16x32_bf16 v[104:107], v[154:157], v[232:235], v[104:107]
	v_mfma_f32_16x16x32_bf16 v[96:99], v[158:161], v[228:231], v[96:99]
	v_mfma_f32_16x16x32_bf16 v[96:99], v[162:165], v[232:235], v[96:99]
	v_mfma_f32_16x16x32_bf16 v[84:87], v[166:169], v[228:231], v[84:87]
	v_mfma_f32_16x16x32_bf16 v[84:87], v[170:173], v[232:235], v[84:87]
	v_mfma_f32_16x16x32_bf16 v[76:79], v[174:177], v[228:231], v[76:79]
	v_mfma_f32_16x16x32_bf16 v[76:79], v[178:181], v[232:235], v[76:79]
	v_mfma_f32_16x16x32_bf16 v[88:91], v[150:153], v[236:239], v[88:91]
	v_mfma_f32_16x16x32_bf16 v[88:91], v[154:157], v[240:243], v[88:91]
	v_mfma_f32_16x16x32_bf16 v[80:83], v[158:161], v[236:239], v[80:83]
	v_mfma_f32_16x16x32_bf16 v[80:83], v[162:165], v[240:243], v[80:83]
	v_mfma_f32_16x16x32_bf16 v[72:75], v[166:169], v[236:239], v[72:75]
	v_mfma_f32_16x16x32_bf16 v[72:75], v[170:173], v[240:243], v[72:75]
	v_mfma_f32_16x16x32_bf16 v[68:71], v[174:177], v[236:239], v[68:71]
	v_mfma_f32_16x16x32_bf16 v[68:71], v[178:181], v[240:243], v[68:71]
	s_setprio 0
	s_barrier
; #define PG8_STAGE(bufoff, gbase, voff) do { _Pragma("unroll") for (int _i = 0; _i < 2; ++_i) \
;         __builtin_amdgcn_global_load_lds((const unsigned*)((const char*)(gbase) + (voff)[_i]), (PG8_LAS unsigned*)(lds + (bufoff) + ldsw + _i * 8192), 16, 0, 0); } while (0)
; #define PG8_LDA(dst, b, h) do { _Pragma("unroll") for (int m = 0; m < 4; ++m) _Pragma("unroll") for (int k = 0; k < 2; ++k) dst[m][k] = *(const PG8_LAS bf16x8*)(lds + PG8_SA(b, h) + aoff + m * 2048 + k * 1024); } while (0)
; #define PG8_MMA(ai, bj, At, Bt) do { __builtin_amdgcn_s_setprio(1); _Pragma("unroll") for (int m = 0; m < 4; ++m) _Pragma("unroll") for (int n = 0; n < 2; ++n) _Pragma("unroll") for (int k = 0; k < 2; ++k) \
;         acc[ai][bj][m][n] = __builtin_amdgcn_mfma_f32_16x16x32_bf16(Bt[n][k], At[m][k], acc[ai][bj][m][n], 0, 0, 0); __builtin_amdgcn_s_setprio(0); } while (0)
; #define PG8_WAIT_V(n) asm volatile("s_waitcnt vmcnt(" #n ")" ::: "memory")
; #define PG8_WAIT_L(n) asm volatile("s_waitcnt lgkmcnt(" #n ")" ::: "memory")
; #define PG8_BAR __builtin_amdgcn_s_barrier()
; #define PG8_SCHED __builtin_amdgcn_sched_barrier(0)
; template <class Epi, class Sched, bool ALIGN_EPI = false, bool SP2 = false>
; __device__ __forceinline__ void gemm_phase(PG8_LAS unsigned char* lds, const Gemm g, const Sched& S, const Epi& E) {
;     ...
;         for (int t = 0; t < nt; t += 2) {
;             const bool last = (t == nt - 2);
;             const char* a1 = cA + (size_t)(t + 1) * kstep;
;             const char* a2 = last ? nA : cA + (size_t)(t + 2) * kstep; const char* b2 = last ? nB : cB + (size_t)(t + 2) * kstep;
;     ...
;             PG8_LDA(At, 1, 1); PG8_STAGE(PG8_SB(1, 0), b3, voffB); PG8_STAGE(PG8_SB(1, 1), b3 + hstep, voffB); PG8_STAGE(PG8_SA(1, 0), a3, voffA);
;             PG8_WAIT_V(8); PG8_WAIT_L(0); PG8_BAR; PG8_MMA(1, 0, At, B0); PG8_MMA(1, 1, At, B1); PG8_BAR; PG8_SCHED;
;     ...
;         if constexpr (ALIGN_EPI) { if (wr == 0) PG8_BAR; }
	s_add_i32 s18, s44, s23
	v_lshl_add_u64 v[144:145], v[144:145], 0, s[34:35]
	s_mov_b32 m0, s18
	ds_read_b128 v[198:201], v148 offset:49152
	ds_read_b128 v[202:205], v148 offset:50176
	ds_read_b128 v[220:223], v148 offset:51200
	ds_read_b128 v[224:227], v148 offset:52224
	ds_read_b128 v[228:231], v148 offset:53248
	ds_read_b128 v[232:235], v148 offset:54272
	ds_read_b128 v[236:239], v148 offset:55296
	ds_read_b128 v[240:243], v148 offset:56320
	global_load_lds_dwordx4 v[144:145], off
	s_add_i32 m0, s18, 0x2000
	s_add_u32 s16, s16, 0x80080
	v_lshl_add_u64 v[144:145], v[184:185], 0, s[34:35]
	s_addc_u32 s17, s17, 0
	s_add_i32 s18, s45, s23
	global_load_lds_dwordx4 v[144:145], off
	v_lshl_add_u64 v[144:145], s[16:17], 0, v[2:3]
	s_mov_b32 m0, s18
	s_nop 0
	global_load_lds_dwordx4 v[144:145], off
	v_lshl_add_u64 v[144:145], s[16:17], 0, v[132:133]
	s_add_i32 m0, s18, 0x2000
	s_nop 0
	global_load_lds_dwordx4 v[144:145], off
	v_lshl_add_u64 v[144:145], v[186:187], 0, s[34:35]
	s_mov_b32 m0, s28
	s_nop 0
	global_load_lds_dwordx4 v[144:145], off
	v_lshl_add_u64 v[144:145], v[196:197], 0, s[34:35]
	s_mov_b32 m0, s29
	s_nop 0
	global_load_lds_dwordx4 v[144:145], off
	s_waitcnt vmcnt(8)
	s_waitcnt lgkmcnt(0)
	s_barrier
	s_setprio 1
	s_waitcnt lgkmcnt(0)
	v_mfma_f32_16x16x32_bf16 v[64:67], v[150:153], v[198:201], v[64:67]
	v_mfma_f32_16x16x32_bf16 v[64:67], v[154:157], v[202:205], v[64:67]
	v_mfma_f32_16x16x32_bf16 v[60:63], v[158:161], v[198:201], v[60:63]
	v_mfma_f32_16x16x32_bf16 v[60:63], v[162:165], v[202:205], v[60:63]
	v_mfma_f32_16x16x32_bf16 v[52:55], v[166:169], v[198:201], v[52:55]
	v_mfma_f32_16x16x32_bf16 v[52:55], v[170:173], v[202:205], v[52:55]
	v_mfma_f32_16x16x32_bf16 v[44:47], v[174:177], v[198:201], v[44:47]
	v_mfma_f32_16x16x32_bf16 v[44:47], v[178:181], v[202:205], v[44:47]
	v_mfma_f32_16x16x32_bf16 v[56:59], v[150:153], v[220:223], v[56:59]
	v_mfma_f32_16x16x32_bf16 v[56:59], v[154:157], v[224:227], v[56:59]
	v_mfma_f32_16x16x32_bf16 v[48:51], v[158:161], v[220:223], v[48:51]
	v_mfma_f32_16x16x32_bf16 v[48:51], v[162:165], v[224:227], v[48:51]
	v_mfma_f32_16x16x32_bf16 v[36:39], v[166:169], v[220:223], v[36:39]
	v_mfma_f32_16x16x32_bf16 v[36:39], v[170:173], v[224:227], v[36:39]
	v_mfma_f32_16x16x32_bf16 v[28:31], v[174:177], v[220:223], v[28:31]
	v_mfma_f32_16x16x32_bf16 v[28:31], v[178:181], v[224:227], v[28:31]
	s_setprio 0
	s_setprio 1
	v_mfma_f32_16x16x32_bf16 v[40:43], v[150:153], v[228:231], v[40:43]
	v_mfma_f32_16x16x32_bf16 v[40:43], v[154:157], v[232:235], v[40:43]
	v_mfma_f32_16x16x32_bf16 v[32:35], v[158:161], v[228:231], v[32:35]
	v_mfma_f32_16x16x32_bf16 v[32:35], v[162:165], v[232:235], v[32:35]
	v_mfma_f32_16x16x32_bf16 v[20:23], v[166:169], v[228:231], v[20:23]
	v_mfma_f32_16x16x32_bf16 v[20:23], v[170:173], v[232:235], v[20:23]
	v_mfma_f32_16x16x32_bf16 v[12:15], v[174:177], v[228:231], v[12:15]
	v_mfma_f32_16x16x32_bf16 v[12:15], v[178:181], v[232:235], v[12:15]
	v_mfma_f32_16x16x32_bf16 v[24:27], v[150:153], v[236:239], v[24:27]
	v_mfma_f32_16x16x32_bf16 v[24:27], v[154:157], v[240:243], v[24:27]
	v_mfma_f32_16x16x32_bf16 v[16:19], v[158:161], v[236:239], v[16:19]
	v_mfma_f32_16x16x32_bf16 v[16:19], v[162:165], v[240:243], v[16:19]
	v_mfma_f32_16x16x32_bf16 v[8:11], v[166:169], v[236:239], v[8:11]
	v_mfma_f32_16x16x32_bf16 v[8:11], v[170:173], v[240:243], v[8:11]
	v_mfma_f32_16x16x32_bf16 v[4:7], v[174:177], v[236:239], v[4:7]
	v_mfma_f32_16x16x32_bf16 v[4:7], v[178:181], v[240:243], v[4:7]
	s_setprio 0
	s_barrier
	s_add_i32 s43, s43, 2
	s_add_u32 s14, s14, 0x100
	s_addc_u32 s15, s15, 0
	s_add_u32 s41, s41, 0x100
	s_addc_u32 s42, s42, 0
	s_cmp_gt_u32 s43, 29
	s_cbranch_scc0 .LBB11_913
	s_and_b64 vcc, exec, s[4:5]
	s_cbranch_vccz .LBB11_916
	s_barrier

; #define PG8_STAGE(bufoff, gbase, voff) do { _Pragma("unroll") for (int _i = 0; _i < 2; ++_i) \
;         __builtin_amdgcn_global_load_lds((const unsigned*)((const char*)(gbase) + (voff)[_i]), (PG8_LAS unsigned*)(lds + (bufoff) + ldsw + _i * 8192), 16, 0, 0); } while (0)
; #define PG8_LDA(dst, b, h) do { _Pragma("unroll") for (int m = 0; m < 4; ++m) _Pragma("unroll") for (int k = 0; k < 2; ++k) dst[m][k] = *(const PG8_LAS bf16x8*)(lds + PG8_SA(b, h) + aoff + m * 2048 + k * 1024); } while (0)
; #define PG8_LDB(dst, b, h) do { _Pragma("unroll") for (int n = 0; n < 2; ++n) _Pragma("unroll") for (int k = 0; k < 2; ++k) dst[n][k] = *(const PG8_LAS bf16x8*)(lds + PG8_SB(b, h) + boff + n * 2048 + k * 1024); } while (0)
; #define PG8_WAIT_V(n) asm volatile("s_waitcnt vmcnt(" #n ")" ::: "memory")
; #define PG8_WAIT_L(n) asm volatile("s_waitcnt lgkmcnt(" #n ")" ::: "memory")
; #define PG8_BAR __builtin_amdgcn_s_barrier()
; #define PG8_SCHED __builtin_amdgcn_sched_barrier(0)
; template <class Epi, class Sched, bool ALIGN_EPI = false, bool SP2 = false>
; __device__ __forceinline__ void gemm_phase(PG8_LAS unsigned char* lds, const Gemm g, const Sched& S, const Epi& E) {
;     ...
;         const char* nA = has_next ? (const char*)g.A + (size_t)nxt.pm * tstep : cA; const char* nB = has_next ? (const char*)g.Bt + (size_t)nxt.pn * tstep : cB;
;         for (int t = 0; t < nt; t += 2) {
;             const bool last = (t == nt - 2);
;             const char* a1 = cA + (size_t)(t + 1) * kstep;
;             const char* a2 = last ? nA : cA + (size_t)(t + 2) * kstep; const char* b2 = last ? nB : cB + (size_t)(t + 2) * kstep;
;             const char* a3 = a2 + kstep; const char* b3 = b2 + kstep;
;             if (last && has_next) S.a_ready(nxt);
;             if constexpr (SP2) {
;             PG8_LDB(B0, 0, 0); PG8_LDB(B1, 0, 1); PG8_SCHED; PG8_LDA(At, 0, 0); PG8_STAGE(PG8_SA(1, 1), a1 + hstep, voffA);
;             PG8_WAIT_V(8); PG8_WAIT_L(0); PG8_BAR; PG8_MMA(0, 0, At, B0); PG8_MMA(0, 1, At, B1); PG8_BAR; PG8_SCHED;
;             PG8_LDA(At, 0, 1); PG8_STAGE(PG8_SB(0, 0), b2, voffB); PG8_STAGE(PG8_SB(0, 1), b2 + hstep, voffB); PG8_STAGE(PG8_SA(0, 0), a2, voffA);
;             PG8_WAIT_V(8); PG8_WAIT_L(0); PG8_BAR; PG8_MMA(1, 0, At, B0); PG8_MMA(1, 1, At, B1); PG8_BAR; PG8_SCHED;
.LBB11_1071:
	s_add_u32 s16, s14, 0xfff80080
	s_addc_u32 s17, s15, -1
	s_add_i32 s46, 0, 0x10000
	s_cmp_eq_u32 s45, 28
	s_cselect_b32 s19, s9, s17
	s_cselect_b32 s18, s41, s16
	v_add_u32_e32 v2, s46, v168
	s_cselect_b32 s17, s7, s44
	s_cselect_b32 s16, s42, s43
	s_add_i32 s48, 0, 0x14000
	ds_read_b128 v[132:135], v2
	ds_read_b128 v[136:139], v2 offset:1024
	ds_read_b128 v[140:143], v2 offset:2048
	ds_read_b128 v[144:147], v2 offset:3072
	v_add_u32_e32 v2, s48, v168
	ds_read_b128 v[170:173], v2
	ds_read_b128 v[174:177], v2 offset:1024
	ds_read_b128 v[178:181], v2 offset:2048
	ds_read_b128 v[198:201], v2 offset:3072
	v_lshl_add_u64 v[166:167], s[14:15], 0, v[162:163]
	s_add_i32 m0, s25, 0xc000
	ds_read_b128 v[202:205], v169
	ds_read_b128 v[220:223], v169 offset:1024
	ds_read_b128 v[224:227], v169 offset:2048
	ds_read_b128 v[228:231], v169 offset:3072
	ds_read_b128 v[232:235], v169 offset:4096
	ds_read_b128 v[236:239], v169 offset:5120
	ds_read_b128 v[240:243], v169 offset:6144
	ds_read_b128 v[244:247], v169 offset:7168
	global_load_lds_dwordx4 v[166:167], off
	v_lshl_add_u64 v[166:167], s[14:15], 0, v[164:165]
	s_add_i32 m0, s25, 0xe000
	s_nop 0
	global_load_lds_dwordx4 v[166:167], off
	s_waitcnt vmcnt(8)
	s_waitcnt lgkmcnt(0)
	s_barrier
	s_setprio 1
	s_waitcnt lgkmcnt(0)
	v_mfma_f32_16x16x32_bf16 v[128:131], v[132:135], v[202:205], v[128:131]
	v_mfma_f32_16x16x32_bf16 v[128:131], v[136:139], v[220:223], v[128:131]
	v_mfma_f32_16x16x32_bf16 v[124:127], v[140:143], v[202:205], v[124:127]
	v_mfma_f32_16x16x32_bf16 v[124:127], v[144:147], v[220:223], v[124:127]
	v_mfma_f32_16x16x32_bf16 v[116:119], v[170:173], v[202:205], v[116:119]
	v_mfma_f32_16x16x32_bf16 v[116:119], v[174:177], v[220:223], v[116:119]
	v_mfma_f32_16x16x32_bf16 v[108:111], v[178:181], v[202:205], v[108:111]
	v_mfma_f32_16x16x32_bf16 v[108:111], v[198:201], v[220:223], v[108:111]
	v_mfma_f32_16x16x32_bf16 v[120:123], v[132:135], v[224:227], v[120:123]
	v_mfma_f32_16x16x32_bf16 v[120:123], v[136:139], v[228:231], v[120:123]
	v_mfma_f32_16x16x32_bf16 v[112:115], v[140:143], v[224:227], v[112:115]
	v_mfma_f32_16x16x32_bf16 v[112:115], v[144:147], v[228:231], v[112:115]
	v_mfma_f32_16x16x32_bf16 v[100:103], v[170:173], v[224:227], v[100:103]
	v_mfma_f32_16x16x32_bf16 v[100:103], v[174:177], v[228:231], v[100:103]
	v_mfma_f32_16x16x32_bf16 v[92:95], v[178:181], v[224:227], v[92:95]
	v_mfma_f32_16x16x32_bf16 v[92:95], v[198:201], v[228:231], v[92:95]
	s_setprio 0
	s_setprio 1
	v_mfma_f32_16x16x32_bf16 v[104:107], v[132:135], v[232:235], v[104:107]
	v_mfma_f32_16x16x32_bf16 v[104:107], v[136:139], v[236:239], v[104:107]
	v_mfma_f32_16x16x32_bf16 v[96:99], v[140:143], v[232:235], v[96:99]
	v_mfma_f32_16x16x32_bf16 v[96:99], v[144:147], v[236:239], v[96:99]
	v_mfma_f32_16x16x32_bf16 v[84:87], v[170:173], v[232:235], v[84:87]
	v_mfma_f32_16x16x32_bf16 v[84:87], v[174:177], v[236:239], v[84:87]
	v_mfma_f32_16x16x32_bf16 v[76:79], v[178:181], v[232:235], v[76:79]
	v_mfma_f32_16x16x32_bf16 v[76:79], v[198:201], v[236:239], v[76:79]
	v_mfma_f32_16x16x32_bf16 v[88:91], v[132:135], v[240:243], v[88:91]
	v_mfma_f32_16x16x32_bf16 v[88:91], v[136:139], v[244:247], v[88:91]
	v_mfma_f32_16x16x32_bf16 v[80:83], v[140:143], v[240:243], v[80:83]
	v_mfma_f32_16x16x32_bf16 v[80:83], v[144:147], v[244:247], v[80:83]
	v_mfma_f32_16x16x32_bf16 v[72:75], v[170:173], v[240:243], v[72:75]
	v_mfma_f32_16x16x32_bf16 v[72:75], v[174:177], v[244:247], v[72:75]
	v_mfma_f32_16x16x32_bf16 v[68:71], v[178:181], v[240:243], v[68:71]
	v_mfma_f32_16x16x32_bf16 v[68:71], v[198:201], v[244:247], v[68:71]
	s_setprio 0
	s_barrier
	s_add_i32 s46, s46, s24
	v_lshl_add_u64 v[166:167], s[16:17], 0, v[154:155]
	s_mov_b32 m0, s46
	ds_read_b128 v[202:205], v169 offset:16384
	ds_read_b128 v[220:223], v169 offset:17408
	ds_read_b128 v[224:227], v169 offset:18432
	ds_read_b128 v[228:231], v169 offset:19456
	ds_read_b128 v[232:235], v169 offset:20480
	ds_read_b128 v[236:239], v169 offset:21504
	ds_read_b128 v[240:243], v169 offset:22528
	ds_read_b128 v[244:247], v169 offset:23552
	global_load_lds_dwordx4 v[166:167], off
	s_add_i32 m0, s46, 0x2000
	s_add_u32 s46, s16, 0x80000
	v_lshl_add_u64 v[196:197], s[16:17], 0, v[150:151]
	s_addc_u32 s47, s17, 0
	s_add_i32 s48, s48, s24
	global_load_lds_dwordx4 v[196:197], off
	v_lshl_add_u64 v[206:207], s[46:47], 0, v[154:155]
	s_mov_b32 m0, s48
	v_lshl_add_u64 v[184:185], s[18:19], 0, v[152:153]
	global_load_lds_dwordx4 v[206:207], off
	v_lshl_add_u64 v[206:207], s[46:47], 0, v[150:151]
	s_add_i32 m0, s48, 0x2000
	s_nop 0
	global_load_lds_dwordx4 v[206:207], off
	v_lshl_add_u64 v[206:207], s[18:19], 0, v[156:157]
	s_mov_b32 m0, s25
	s_nop 0
	global_load_lds_dwordx4 v[206:207], off
	s_mov_b32 m0, s26
	s_nop 0
	global_load_lds_dwordx4 v[184:185], off
	s_waitcnt vmcnt(8)
	s_waitcnt lgkmcnt(0)
	s_barrier
; #define PG8_STAGE(bufoff, gbase, voff) do { _Pragma("unroll") for (int _i = 0; _i < 2; ++_i) \
;         __builtin_amdgcn_global_load_lds((const unsigned*)((const char*)(gbase) + (voff)[_i]), (PG8_LAS unsigned*)(lds + (bufoff) + ldsw + _i * 8192), 16, 0, 0); } while (0)
; #define PG8_LDA(dst, b, h) do { _Pragma("unroll") for (int m = 0; m < 4; ++m) _Pragma("unroll") for (int k = 0; k < 2; ++k) dst[m][k] = *(const PG8_LAS bf16x8*)(lds + PG8_SA(b, h) + aoff + m * 2048 + k * 1024); } while (0)
; #define PG8_LDB(dst, b, h) do { _Pragma("unroll") for (int n = 0; n < 2; ++n) _Pragma("unroll") for (int k = 0; k < 2; ++k) dst[n][k] = *(const PG8_LAS bf16x8*)(lds + PG8_SB(b, h) + boff + n * 2048 + k * 1024); } while (0)
; #define PG8_MMA(ai, bj, At, Bt) do { __builtin_amdgcn_s_setprio(1); _Pragma("unroll") for (int m = 0; m < 4; ++m) _Pragma("unroll") for (int n = 0; n < 2; ++n) _Pragma("unroll") for (int k = 0; k < 2; ++k) \
;         acc[ai][bj][m][n] = __builtin_amdgcn_mfma_f32_16x16x32_bf16(Bt[n][k], At[m][k], acc[ai][bj][m][n], 0, 0, 0); __builtin_amdgcn_s_setprio(0); } while (0)
; #define PG8_WAIT_V(n) asm volatile("s_waitcnt vmcnt(" #n ")" ::: "memory")
; #define PG8_WAIT_L(n) asm volatile("s_waitcnt lgkmcnt(" #n ")" ::: "memory")
; #define PG8_BAR __builtin_amdgcn_s_barrier()
; #define PG8_SCHED __builtin_amdgcn_sched_barrier(0)
; template <class Epi, class Sched, bool ALIGN_EPI = false, bool SP2 = false>
; __device__ __forceinline__ void gemm_phase(PG8_LAS unsigned char* lds, const Gemm g, const Sched& S, const Epi& E) {
;     ...
;             PG8_WAIT_V(8); PG8_WAIT_L(0); PG8_BAR; PG8_MMA(1, 0, At, B0); PG8_MMA(1, 1, At, B1); PG8_BAR; PG8_SCHED;
;             PG8_LDB(B0, 1, 0); PG8_LDB(B1, 1, 1); PG8_SCHED; PG8_LDA(At, 1, 0); PG8_STAGE(PG8_SA(0, 1), a2 + hstep, voffA);
;             PG8_WAIT_V(8); PG8_WAIT_L(0); PG8_BAR; PG8_MMA(0, 0, At, B0); PG8_MMA(0, 1, At, B1); PG8_BAR; PG8_SCHED;
;             PG8_LDA(At, 1, 1); PG8_STAGE(PG8_SB(1, 0), b3, voffB); PG8_STAGE(PG8_SB(1, 1), b3 + hstep, voffB); PG8_STAGE(PG8_SA(1, 0), a3, voffA);
	s_setprio 1
	s_waitcnt lgkmcnt(0)
	v_mfma_f32_16x16x32_bf16 v[64:67], v[132:135], v[202:205], v[64:67]
	v_mfma_f32_16x16x32_bf16 v[64:67], v[136:139], v[220:223], v[64:67]
	v_mfma_f32_16x16x32_bf16 v[60:63], v[140:143], v[202:205], v[60:63]
	v_mfma_f32_16x16x32_bf16 v[60:63], v[144:147], v[220:223], v[60:63]
	v_mfma_f32_16x16x32_bf16 v[52:55], v[170:173], v[202:205], v[52:55]
	v_mfma_f32_16x16x32_bf16 v[52:55], v[174:177], v[220:223], v[52:55]
	v_mfma_f32_16x16x32_bf16 v[44:47], v[178:181], v[202:205], v[44:47]
	v_mfma_f32_16x16x32_bf16 v[44:47], v[198:201], v[220:223], v[44:47]
	v_mfma_f32_16x16x32_bf16 v[56:59], v[132:135], v[224:227], v[56:59]
	v_mfma_f32_16x16x32_bf16 v[56:59], v[136:139], v[228:231], v[56:59]
	v_mfma_f32_16x16x32_bf16 v[48:51], v[140:143], v[224:227], v[48:51]
	v_mfma_f32_16x16x32_bf16 v[48:51], v[144:147], v[228:231], v[48:51]
	v_mfma_f32_16x16x32_bf16 v[36:39], v[170:173], v[224:227], v[36:39]
	v_mfma_f32_16x16x32_bf16 v[36:39], v[174:177], v[228:231], v[36:39]
	v_mfma_f32_16x16x32_bf16 v[28:31], v[178:181], v[224:227], v[28:31]
	v_mfma_f32_16x16x32_bf16 v[28:31], v[198:201], v[228:231], v[28:31]
	s_setprio 0
	s_setprio 1
	v_mfma_f32_16x16x32_bf16 v[40:43], v[132:135], v[232:235], v[40:43]
	v_mfma_f32_16x16x32_bf16 v[40:43], v[136:139], v[236:239], v[40:43]
	v_mfma_f32_16x16x32_bf16 v[32:35], v[140:143], v[232:235], v[32:35]
	v_mfma_f32_16x16x32_bf16 v[32:35], v[144:147], v[236:239], v[32:35]
	v_mfma_f32_16x16x32_bf16 v[20:23], v[170:173], v[232:235], v[20:23]
	v_mfma_f32_16x16x32_bf16 v[20:23], v[174:177], v[236:239], v[20:23]
	v_mfma_f32_16x16x32_bf16 v[12:15], v[178:181], v[232:235], v[12:15]
	v_mfma_f32_16x16x32_bf16 v[12:15], v[198:201], v[236:239], v[12:15]
	v_mfma_f32_16x16x32_bf16 v[24:27], v[132:135], v[240:243], v[24:27]
	v_mfma_f32_16x16x32_bf16 v[24:27], v[136:139], v[244:247], v[24:27]
	v_mfma_f32_16x16x32_bf16 v[16:19], v[140:143], v[240:243], v[16:19]
	v_mfma_f32_16x16x32_bf16 v[16:19], v[144:147], v[244:247], v[16:19]
	v_mfma_f32_16x16x32_bf16 v[8:11], v[170:173], v[240:243], v[8:11]
	v_mfma_f32_16x16x32_bf16 v[8:11], v[174:177], v[244:247], v[8:11]
	v_mfma_f32_16x16x32_bf16 v[4:7], v[178:181], v[240:243], v[4:7]
	v_mfma_f32_16x16x32_bf16 v[4:7], v[198:201], v[244:247], v[4:7]
	s_setprio 0
	s_barrier
	s_add_i32 s46, 0, 0x18000
	v_add_u32_e32 v2, s46, v168
	s_add_i32 s47, 0, 0x1c000
	ds_read_b128 v[132:135], v2
	ds_read_b128 v[136:139], v2 offset:1024
	ds_read_b128 v[140:143], v2 offset:2048
	ds_read_b128 v[144:147], v2 offset:3072
	v_add_u32_e32 v2, s47, v168
	ds_read_b128 v[170:173], v2
	ds_read_b128 v[174:177], v2 offset:1024
	ds_read_b128 v[178:181], v2 offset:2048
	ds_read_b128 v[198:201], v2 offset:3072
	s_add_u32 s18, s18, 0x80000
	s_addc_u32 s19, s19, 0
	s_mov_b32 m0, s27
	v_lshl_add_u64 v[186:187], s[18:19], 0, v[156:157]
	ds_read_b128 v[202:205], v169 offset:32768
	ds_read_b128 v[220:223], v169 offset:33792
	ds_read_b128 v[224:227], v169 offset:34816
	ds_read_b128 v[228:231], v169 offset:35840
	ds_read_b128 v[232:235], v169 offset:36864
	ds_read_b128 v[236:239], v169 offset:37888
	ds_read_b128 v[240:243], v169 offset:38912
	ds_read_b128 v[244:247], v169 offset:39936
	global_load_lds_dwordx4 v[186:187], off
	v_lshl_add_u64 v[186:187], s[18:19], 0, v[152:153]
	s_mov_b32 m0, s28
	s_nop 0
	global_load_lds_dwordx4 v[186:187], off
	s_waitcnt vmcnt(8)
	s_waitcnt lgkmcnt(0)
	s_barrier
	s_setprio 1
	s_waitcnt lgkmcnt(0)
	v_mfma_f32_16x16x32_bf16 v[128:131], v[132:135], v[202:205], v[128:131]
	v_mfma_f32_16x16x32_bf16 v[128:131], v[136:139], v[220:223], v[128:131]
	v_mfma_f32_16x16x32_bf16 v[124:127], v[140:143], v[202:205], v[124:127]
	v_mfma_f32_16x16x32_bf16 v[124:127], v[144:147], v[220:223], v[124:127]
	v_mfma_f32_16x16x32_bf16 v[116:119], v[170:173], v[202:205], v[116:119]
	v_mfma_f32_16x16x32_bf16 v[116:119], v[174:177], v[220:223], v[116:119]
	v_mfma_f32_16x16x32_bf16 v[108:111], v[178:181], v[202:205], v[108:111]
	v_mfma_f32_16x16x32_bf16 v[108:111], v[198:201], v[220:223], v[108:111]
	v_mfma_f32_16x16x32_bf16 v[120:123], v[132:135], v[224:227], v[120:123]
	v_mfma_f32_16x16x32_bf16 v[120:123], v[136:139], v[228:231], v[120:123]
	v_mfma_f32_16x16x32_bf16 v[112:115], v[140:143], v[224:227], v[112:115]
	v_mfma_f32_16x16x32_bf16 v[112:115], v[144:147], v[228:231], v[112:115]
	v_mfma_f32_16x16x32_bf16 v[100:103], v[170:173], v[224:227], v[100:103]
	v_mfma_f32_16x16x32_bf16 v[100:103], v[174:177], v[228:231], v[100:103]
	v_mfma_f32_16x16x32_bf16 v[92:95], v[178:181], v[224:227], v[92:95]
	v_mfma_f32_16x16x32_bf16 v[92:95], v[198:201], v[228:231], v[92:95]
	s_setprio 0
	s_setprio 1
	v_mfma_f32_16x16x32_bf16 v[104:107], v[132:135], v[232:235], v[104:107]
	v_mfma_f32_16x16x32_bf16 v[104:107], v[136:139], v[236:239], v[104:107]
	v_mfma_f32_16x16x32_bf16 v[96:99], v[140:143], v[232:235], v[96:99]
	v_mfma_f32_16x16x32_bf16 v[96:99], v[144:147], v[236:239], v[96:99]
	v_mfma_f32_16x16x32_bf16 v[84:87], v[170:173], v[232:235], v[84:87]
	v_mfma_f32_16x16x32_bf16 v[84:87], v[174:177], v[236:239], v[84:87]
	v_mfma_f32_16x16x32_bf16 v[76:79], v[178:181], v[232:235], v[76:79]
	v_mfma_f32_16x16x32_bf16 v[76:79], v[198:201], v[236:239], v[76:79]
	v_mfma_f32_16x16x32_bf16 v[88:91], v[132:135], v[240:243], v[88:91]
	v_mfma_f32_16x16x32_bf16 v[88:91], v[136:139], v[244:247], v[88:91]
	v_mfma_f32_16x16x32_bf16 v[80:83], v[140:143], v[240:243], v[80:83]
	v_mfma_f32_16x16x32_bf16 v[80:83], v[144:147], v[244:247], v[80:83]
	v_mfma_f32_16x16x32_bf16 v[72:75], v[170:173], v[240:243], v[72:75]
	v_mfma_f32_16x16x32_bf16 v[72:75], v[174:177], v[244:247], v[72:75]
	v_mfma_f32_16x16x32_bf16 v[68:71], v[178:181], v[240:243], v[68:71]
	v_mfma_f32_16x16x32_bf16 v[68:71], v[198:201], v[244:247], v[68:71]
	s_setprio 0
	s_barrier
; #define PG8_STAGE(bufoff, gbase, voff) do { _Pragma("unroll") for (int _i = 0; _i < 2; ++_i) \
;         __builtin_amdgcn_global_load_lds((const unsigned*)((const char*)(gbase) + (voff)[_i]), (PG8_LAS unsigned*)(lds + (bufoff) + ldsw + _i * 8192), 16, 0, 0); } while (0)
; #define PG8_LDA(dst, b, h) do { _Pragma("unroll") for (int m = 0; m < 4; ++m) _Pragma("unroll") for (int k = 0; k < 2; ++k) dst[m][k] = *(const PG8_LAS bf16x8*)(lds + PG8_SA(b, h) + aoff + m * 2048 + k * 1024); } while (0)
; #define PG8_MMA(ai, bj, At, Bt) do { __builtin_amdgcn_s_setprio(1); _Pragma("unroll") for (int m = 0; m < 4; ++m) _Pragma("unroll") for (int n = 0; n < 2; ++n) _Pragma("unroll") for (int k = 0; k < 2; ++k) \
;         acc[ai][bj][m][n] = __builtin_amdgcn_mfma_f32_16x16x32_bf16(Bt[n][k], At[m][k], acc[ai][bj][m][n], 0, 0, 0); __builtin_amdgcn_s_setprio(0); } while (0)
; #define PG8_WAIT_V(n) asm volatile("s_waitcnt vmcnt(" #n ")" ::: "memory")
; #define PG8_WAIT_L(n) asm volatile("s_waitcnt lgkmcnt(" #n ")" ::: "memory")
; #define PG8_BAR __builtin_amdgcn_s_barrier()
; #define PG8_SCHED __builtin_amdgcn_sched_barrier(0)
; template <class Epi, class Sched, bool ALIGN_EPI = false, bool SP2 = false>
; __device__ __forceinline__ void gemm_phase(PG8_LAS unsigned char* lds, const Gemm g, const Sched& S, const Epi& E) {
;     ...
;         for (int t = 0; t < nt; t += 2) {
;             const bool last = (t == nt - 2);
;             const char* a1 = cA + (size_t)(t + 1) * kstep;
;             const char* a2 = last ? nA : cA + (size_t)(t + 2) * kstep; const char* b2 = last ? nB : cB + (size_t)(t + 2) * kstep;
;     ...
;             PG8_LDA(At, 1, 1); PG8_STAGE(PG8_SB(1, 0), b3, voffB); PG8_STAGE(PG8_SB(1, 1), b3 + hstep, voffB); PG8_STAGE(PG8_SA(1, 0), a3, voffA);
;             PG8_WAIT_V(8); PG8_WAIT_L(0); PG8_BAR; PG8_MMA(1, 0, At, B0); PG8_MMA(1, 1, At, B1); PG8_BAR; PG8_SCHED;
;     ...
;         if constexpr (ALIGN_EPI) { if (wr == 0) PG8_BAR; }
	s_add_i32 s18, s46, s24
	v_lshl_add_u64 v[166:167], v[166:167], 0, s[34:35]
	s_mov_b32 m0, s18
	ds_read_b128 v[202:205], v169 offset:49152
	ds_read_b128 v[220:223], v169 offset:50176
	ds_read_b128 v[224:227], v169 offset:51200
	ds_read_b128 v[228:231], v169 offset:52224
	ds_read_b128 v[232:235], v169 offset:53248
	ds_read_b128 v[236:239], v169 offset:54272
	ds_read_b128 v[240:243], v169 offset:55296
	ds_read_b128 v[244:247], v169 offset:56320
	global_load_lds_dwordx4 v[166:167], off
	s_add_i32 m0, s18, 0x2000
	s_add_u32 s16, s16, 0x80080
	v_lshl_add_u64 v[166:167], v[196:197], 0, s[34:35]
	s_addc_u32 s17, s17, 0
	s_add_i32 s18, s47, s24
	global_load_lds_dwordx4 v[166:167], off
	v_lshl_add_u64 v[166:167], s[16:17], 0, v[154:155]
	s_mov_b32 m0, s18
	s_nop 0
	global_load_lds_dwordx4 v[166:167], off
	v_lshl_add_u64 v[166:167], s[16:17], 0, v[150:151]
	s_add_i32 m0, s18, 0x2000
	s_nop 0
	global_load_lds_dwordx4 v[166:167], off
	v_lshl_add_u64 v[166:167], v[206:207], 0, s[34:35]
	s_mov_b32 m0, s33
	s_nop 0
	global_load_lds_dwordx4 v[166:167], off
	v_lshl_add_u64 v[166:167], v[184:185], 0, s[34:35]
	s_mov_b32 m0, s38
	s_nop 0
	global_load_lds_dwordx4 v[166:167], off
	s_waitcnt vmcnt(8)
	s_waitcnt lgkmcnt(0)
	s_barrier
	s_setprio 1
	s_waitcnt lgkmcnt(0)
	v_mfma_f32_16x16x32_bf16 v[64:67], v[132:135], v[202:205], v[64:67]
	v_mfma_f32_16x16x32_bf16 v[64:67], v[136:139], v[220:223], v[64:67]
	v_mfma_f32_16x16x32_bf16 v[60:63], v[140:143], v[202:205], v[60:63]
	v_mfma_f32_16x16x32_bf16 v[60:63], v[144:147], v[220:223], v[60:63]
	v_mfma_f32_16x16x32_bf16 v[52:55], v[170:173], v[202:205], v[52:55]
	v_mfma_f32_16x16x32_bf16 v[52:55], v[174:177], v[220:223], v[52:55]
	v_mfma_f32_16x16x32_bf16 v[44:47], v[178:181], v[202:205], v[44:47]
	v_mfma_f32_16x16x32_bf16 v[44:47], v[198:201], v[220:223], v[44:47]
	v_mfma_f32_16x16x32_bf16 v[56:59], v[132:135], v[224:227], v[56:59]
	v_mfma_f32_16x16x32_bf16 v[56:59], v[136:139], v[228:231], v[56:59]
	v_mfma_f32_16x16x32_bf16 v[48:51], v[140:143], v[224:227], v[48:51]
	v_mfma_f32_16x16x32_bf16 v[48:51], v[144:147], v[228:231], v[48:51]
	v_mfma_f32_16x16x32_bf16 v[36:39], v[170:173], v[224:227], v[36:39]
	v_mfma_f32_16x16x32_bf16 v[36:39], v[174:177], v[228:231], v[36:39]
	v_mfma_f32_16x16x32_bf16 v[28:31], v[178:181], v[224:227], v[28:31]
	v_mfma_f32_16x16x32_bf16 v[28:31], v[198:201], v[228:231], v[28:31]
	s_setprio 0
	s_setprio 1
	v_mfma_f32_16x16x32_bf16 v[40:43], v[132:135], v[232:235], v[40:43]
	v_mfma_f32_16x16x32_bf16 v[40:43], v[136:139], v[236:239], v[40:43]
	v_mfma_f32_16x16x32_bf16 v[32:35], v[140:143], v[232:235], v[32:35]
	v_mfma_f32_16x16x32_bf16 v[32:35], v[144:147], v[236:239], v[32:35]
	v_mfma_f32_16x16x32_bf16 v[20:23], v[170:173], v[232:235], v[20:23]
	v_mfma_f32_16x16x32_bf16 v[20:23], v[174:177], v[236:239], v[20:23]
	v_mfma_f32_16x16x32_bf16 v[12:15], v[178:181], v[232:235], v[12:15]
	v_mfma_f32_16x16x32_bf16 v[12:15], v[198:201], v[236:239], v[12:15]
	v_mfma_f32_16x16x32_bf16 v[24:27], v[132:135], v[240:243], v[24:27]
	v_mfma_f32_16x16x32_bf16 v[24:27], v[136:139], v[244:247], v[24:27]
	v_mfma_f32_16x16x32_bf16 v[16:19], v[140:143], v[240:243], v[16:19]
	v_mfma_f32_16x16x32_bf16 v[16:19], v[144:147], v[244:247], v[16:19]
	v_mfma_f32_16x16x32_bf16 v[8:11], v[170:173], v[240:243], v[8:11]
	v_mfma_f32_16x16x32_bf16 v[8:11], v[174:177], v[244:247], v[8:11]
	v_mfma_f32_16x16x32_bf16 v[4:7], v[178:181], v[240:243], v[4:7]
	v_mfma_f32_16x16x32_bf16 v[4:7], v[198:201], v[244:247], v[4:7]
	s_setprio 0
	s_barrier
	s_add_i32 s45, s45, 2
	s_add_u32 s14, s14, 0x100
	s_addc_u32 s15, s15, 0
	s_add_u32 s43, s43, 0x100
	s_addc_u32 s44, s44, 0
	s_cmp_gt_u32 s45, 29
	s_cbranch_scc0 .LBB11_1071
	s_and_b64 vcc, exec, s[4:5]
	s_cbranch_vccz .LBB11_1074
	s_barrier

; #define PG8_STAGE(bufoff, gbase, voff) do { _Pragma("unroll") for (int _i = 0; _i < 2; ++_i) \
;         __builtin_amdgcn_global_load_lds((const unsigned*)((const char*)(gbase) + (voff)[_i]), (PG8_LAS unsigned*)(lds + (bufoff) + ldsw + _i * 8192), 16, 0, 0); } while (0)
; #define PG8_LDA(dst, b, h) do { _Pragma("unroll") for (int m = 0; m < 4; ++m) _Pragma("unroll") for (int k = 0; k < 2; ++k) dst[m][k] = *(const PG8_LAS bf16x8*)(lds + PG8_SA(b, h) + aoff + m * 2048 + k * 1024); } while (0)
; #define PG8_LDB(dst, b, h) do { _Pragma("unroll") for (int n = 0; n < 2; ++n) _Pragma("unroll") for (int k = 0; k < 2; ++k) dst[n][k] = *(const PG8_LAS bf16x8*)(lds + PG8_SB(b, h) + boff + n * 2048 + k * 1024); } while (0)
; #define PG8_WAIT_V(n) asm volatile("s_waitcnt vmcnt(" #n ")" ::: "memory")
; #define PG8_WAIT_L(n) asm volatile("s_waitcnt lgkmcnt(" #n ")" ::: "memory")
; #define PG8_BAR __builtin_amdgcn_s_barrier()
; #define PG8_SCHED __builtin_amdgcn_sched_barrier(0)
; template <class Epi, class Sched, bool ALIGN_EPI = false, bool SP2 = false>
; __device__ __forceinline__ void gemm_phase(PG8_LAS unsigned char* lds, const Gemm g, const Sched& S, const Epi& E) {
;     ...
;         const char* nA = has_next ? (const char*)g.A + (size_t)nxt.pm * tstep : cA; const char* nB = has_next ? (const char*)g.Bt + (size_t)nxt.pn * tstep : cB;
;         for (int t = 0; t < nt; t += 2) {
;             const bool last = (t == nt - 2);
;             const char* a1 = cA + (size_t)(t + 1) * kstep;
;             const char* a2 = last ? nA : cA + (size_t)(t + 2) * kstep; const char* b2 = last ? nB : cB + (size_t)(t + 2) * kstep;
;             const char* a3 = a2 + kstep; const char* b3 = b2 + kstep;
;             if (last && has_next) S.a_ready(nxt);
;             if constexpr (SP2) {
;             PG8_LDB(B0, 0, 0); PG8_LDB(B1, 0, 1); PG8_SCHED; PG8_LDA(At, 0, 0); PG8_STAGE(PG8_SA(1, 1), a1 + hstep, voffA);
;             PG8_WAIT_V(8); PG8_WAIT_L(0); PG8_BAR; PG8_MMA(0, 0, At, B0); PG8_MMA(0, 1, At, B1); PG8_BAR; PG8_SCHED;
;             PG8_LDA(At, 0, 1); PG8_STAGE(PG8_SB(0, 0), b2, voffB); PG8_STAGE(PG8_SB(0, 1), b2 + hstep, voffB); PG8_STAGE(PG8_SA(0, 0), a2, voffA);
;             PG8_WAIT_V(8); PG8_WAIT_L(0); PG8_BAR; PG8_MMA(1, 0, At, B0); PG8_MMA(1, 1, At, B1); PG8_BAR; PG8_SCHED;
.LBB11_1896:
	s_add_i32 s56, s22, 2
	s_add_u32 s57, s16, s20
	s_addc_u32 s23, s17, s21
	s_add_u32 s58, s14, s20
	s_addc_u32 s59, s15, s21
	s_add_i32 s60, 0, 0x10000
	s_cmp_eq_u32 s49, s22
	s_cselect_b32 s23, s5, s23
	s_cselect_b32 s22, s4, s57
	s_cselect_b32 s59, s19, s59
	s_cselect_b32 s58, s18, s58
	s_add_i32 s57, 0, 0x14000
	v_add_u32_e32 v156, s60, v1
	v_add_u32_e32 v174, s57, v1
	ds_read_b128 v[144:147], v156
	ds_read_b128 v[148:151], v156 offset:1024
	ds_read_b128 v[152:155], v156 offset:2048
	ds_read_b128 v[156:159], v156 offset:3072
	ds_read_b128 v[160:163], v174
	ds_read_b128 v[166:169], v174 offset:1024
	ds_read_b128 v[170:173], v174 offset:2048
	ds_read_b128 v[174:177], v174 offset:3072
	v_lshl_add_u64 v[184:185], s[16:17], 0, v[140:141]
	s_add_i32 m0, s45, 0xc000
	ds_read_b128 v[178:181], v143
	ds_read_b128 v[198:201], v143 offset:1024
	ds_read_b128 v[202:205], v143 offset:2048
	ds_read_b128 v[220:223], v143 offset:3072
	ds_read_b128 v[224:227], v143 offset:4096
	ds_read_b128 v[228:231], v143 offset:5120
	ds_read_b128 v[232:235], v143 offset:6144
	ds_read_b128 v[236:239], v143 offset:7168
	global_load_lds_dwordx4 v[184:185], off
	v_lshl_add_u64 v[184:185], s[16:17], 0, v[138:139]
	s_add_i32 m0, s45, 0xe000
	s_nop 0
	global_load_lds_dwordx4 v[184:185], off
	s_waitcnt vmcnt(8)
	s_waitcnt lgkmcnt(0)
	s_barrier
	s_setprio 1
	s_waitcnt lgkmcnt(0)
	v_mfma_f32_16x16x32_bf16 v[100:103], v[144:147], v[178:181], v[100:103]
	v_mfma_f32_16x16x32_bf16 v[100:103], v[148:151], v[198:201], v[100:103]
	v_mfma_f32_16x16x32_bf16 v[68:71], v[152:155], v[178:181], v[68:71]
	v_mfma_f32_16x16x32_bf16 v[68:71], v[156:159], v[198:201], v[68:71]
	v_mfma_f32_16x16x32_bf16 v[16:19], v[160:163], v[178:181], v[16:19]
	v_mfma_f32_16x16x32_bf16 v[16:19], v[166:169], v[198:201], v[16:19]
	v_mfma_f32_16x16x32_bf16 v[4:7], v[170:173], v[178:181], v[4:7]
	v_mfma_f32_16x16x32_bf16 v[4:7], v[174:177], v[198:201], v[4:7]
	v_mfma_f32_16x16x32_bf16 v[116:119], v[144:147], v[202:205], v[116:119]
	v_mfma_f32_16x16x32_bf16 v[116:119], v[148:151], v[220:223], v[116:119]
	v_mfma_f32_16x16x32_bf16 v[80:83], v[152:155], v[202:205], v[80:83]
	v_mfma_f32_16x16x32_bf16 v[80:83], v[156:159], v[220:223], v[80:83]
	v_mfma_f32_16x16x32_bf16 v[32:35], v[160:163], v[202:205], v[32:35]
	v_mfma_f32_16x16x32_bf16 v[32:35], v[166:169], v[220:223], v[32:35]
	v_mfma_f32_16x16x32_bf16 v[8:11], v[170:173], v[202:205], v[8:11]
	v_mfma_f32_16x16x32_bf16 v[8:11], v[174:177], v[220:223], v[8:11]
	s_setprio 0
	s_setprio 1
	v_mfma_f32_16x16x32_bf16 v[124:127], v[144:147], v[224:227], v[124:127]
	v_mfma_f32_16x16x32_bf16 v[124:127], v[148:151], v[228:231], v[124:127]
	v_mfma_f32_16x16x32_bf16 v[104:107], v[152:155], v[224:227], v[104:107]
	v_mfma_f32_16x16x32_bf16 v[104:107], v[156:159], v[228:231], v[104:107]
	v_mfma_f32_16x16x32_bf16 v[48:51], v[160:163], v[224:227], v[48:51]
	v_mfma_f32_16x16x32_bf16 v[48:51], v[166:169], v[228:231], v[48:51]
	v_mfma_f32_16x16x32_bf16 v[12:15], v[170:173], v[224:227], v[12:15]
	v_mfma_f32_16x16x32_bf16 v[12:15], v[174:177], v[228:231], v[12:15]
	v_mfma_f32_16x16x32_bf16 v[128:131], v[144:147], v[232:235], v[128:131]
	v_mfma_f32_16x16x32_bf16 v[128:131], v[148:151], v[236:239], v[128:131]
	v_mfma_f32_16x16x32_bf16 v[120:123], v[152:155], v[232:235], v[120:123]
	v_mfma_f32_16x16x32_bf16 v[120:123], v[156:159], v[236:239], v[120:123]
	v_mfma_f32_16x16x32_bf16 v[76:79], v[160:163], v[232:235], v[76:79]
	v_mfma_f32_16x16x32_bf16 v[76:79], v[166:169], v[236:239], v[76:79]
	v_mfma_f32_16x16x32_bf16 v[24:27], v[170:173], v[232:235], v[24:27]
	v_mfma_f32_16x16x32_bf16 v[24:27], v[174:177], v[236:239], v[24:27]
	s_setprio 0
	s_barrier
	s_add_i32 s60, s60, s13
	v_lshl_add_u64 v[184:185], s[58:59], 0, v[2:3]
	s_mov_b32 m0, s60
	ds_read_b128 v[178:181], v143 offset:16384
	ds_read_b128 v[198:201], v143 offset:17408
	ds_read_b128 v[202:205], v143 offset:18432
	ds_read_b128 v[220:223], v143 offset:19456
	ds_read_b128 v[224:227], v143 offset:20480
	ds_read_b128 v[228:231], v143 offset:21504
	ds_read_b128 v[232:235], v143 offset:22528
	ds_read_b128 v[236:239], v143 offset:23552
	global_load_lds_dwordx4 v[184:185], off
	s_add_i32 m0, s60, 0x2000
	v_lshl_add_u64 v[186:187], s[58:59], 0, v[132:133]
	s_add_u32 s58, s58, s33
	s_addc_u32 s59, s59, 0
	s_add_i32 s57, s57, s13
	global_load_lds_dwordx4 v[186:187], off
	v_lshl_add_u64 v[196:197], s[58:59], 0, v[2:3]
	s_mov_b32 m0, s57
	v_lshl_add_u64 v[206:207], s[58:59], 0, v[132:133]
	global_load_lds_dwordx4 v[196:197], off
	s_add_i32 m0, s57, 0x2000
	v_lshl_add_u64 v[240:241], s[22:23], 0, v[2:3]
	global_load_lds_dwordx4 v[206:207], off
	s_mov_b32 m0, s45
	v_lshl_add_u64 v[242:243], s[22:23], 0, v[132:133]
	global_load_lds_dwordx4 v[240:241], off
	s_mov_b32 m0, s46
	s_nop 0
	global_load_lds_dwordx4 v[242:243], off
	s_waitcnt vmcnt(8)
	s_waitcnt lgkmcnt(0)
	s_barrier
; #define PG8_STAGE(bufoff, gbase, voff) do { _Pragma("unroll") for (int _i = 0; _i < 2; ++_i) \
;         __builtin_amdgcn_global_load_lds((const unsigned*)((const char*)(gbase) + (voff)[_i]), (PG8_LAS unsigned*)(lds + (bufoff) + ldsw + _i * 8192), 16, 0, 0); } while (0)
; #define PG8_LDA(dst, b, h) do { _Pragma("unroll") for (int m = 0; m < 4; ++m) _Pragma("unroll") for (int k = 0; k < 2; ++k) dst[m][k] = *(const PG8_LAS bf16x8*)(lds + PG8_SA(b, h) + aoff + m * 2048 + k * 1024); } while (0)
; #define PG8_LDB(dst, b, h) do { _Pragma("unroll") for (int n = 0; n < 2; ++n) _Pragma("unroll") for (int k = 0; k < 2; ++k) dst[n][k] = *(const PG8_LAS bf16x8*)(lds + PG8_SB(b, h) + boff + n * 2048 + k * 1024); } while (0)
; #define PG8_MMA(ai, bj, At, Bt) do { __builtin_amdgcn_s_setprio(1); _Pragma("unroll") for (int m = 0; m < 4; ++m) _Pragma("unroll") for (int n = 0; n < 2; ++n) _Pragma("unroll") for (int k = 0; k < 2; ++k) \
;         acc[ai][bj][m][n] = __builtin_amdgcn_mfma_f32_16x16x32_bf16(Bt[n][k], At[m][k], acc[ai][bj][m][n], 0, 0, 0); __builtin_amdgcn_s_setprio(0); } while (0)
; #define PG8_WAIT_V(n) asm volatile("s_waitcnt vmcnt(" #n ")" ::: "memory")
; #define PG8_WAIT_L(n) asm volatile("s_waitcnt lgkmcnt(" #n ")" ::: "memory")
; #define PG8_BAR __builtin_amdgcn_s_barrier()
; #define PG8_SCHED __builtin_amdgcn_sched_barrier(0)
; template <class Epi, class Sched, bool ALIGN_EPI = false, bool SP2 = false>
; __device__ __forceinline__ void gemm_phase(PG8_LAS unsigned char* lds, const Gemm g, const Sched& S, const Epi& E) {
;     ...
;             PG8_WAIT_V(8); PG8_WAIT_L(0); PG8_BAR; PG8_MMA(1, 0, At, B0); PG8_MMA(1, 1, At, B1); PG8_BAR; PG8_SCHED;
;             PG8_LDB(B0, 1, 0); PG8_LDB(B1, 1, 1); PG8_SCHED; PG8_LDA(At, 1, 0); PG8_STAGE(PG8_SA(0, 1), a2 + hstep, voffA);
;             PG8_WAIT_V(8); PG8_WAIT_L(0); PG8_BAR; PG8_MMA(0, 0, At, B0); PG8_MMA(0, 1, At, B1); PG8_BAR; PG8_SCHED;
	s_setprio 1
	s_waitcnt lgkmcnt(0)
	v_mfma_f32_16x16x32_bf16 v[108:111], v[144:147], v[178:181], v[108:111]
	v_mfma_f32_16x16x32_bf16 v[108:111], v[148:151], v[198:201], v[108:111]
	v_mfma_f32_16x16x32_bf16 v[112:115], v[152:155], v[178:181], v[112:115]
	v_mfma_f32_16x16x32_bf16 v[112:115], v[156:159], v[198:201], v[112:115]
	v_mfma_f32_16x16x32_bf16 v[96:99], v[160:163], v[178:181], v[96:99]
	v_mfma_f32_16x16x32_bf16 v[96:99], v[166:169], v[198:201], v[96:99]
	v_mfma_f32_16x16x32_bf16 v[44:47], v[170:173], v[178:181], v[44:47]
	v_mfma_f32_16x16x32_bf16 v[44:47], v[174:177], v[198:201], v[44:47]
	v_mfma_f32_16x16x32_bf16 v[88:91], v[144:147], v[202:205], v[88:91]
	v_mfma_f32_16x16x32_bf16 v[88:91], v[148:151], v[220:223], v[88:91]
	v_mfma_f32_16x16x32_bf16 v[92:95], v[152:155], v[202:205], v[92:95]
	v_mfma_f32_16x16x32_bf16 v[92:95], v[156:159], v[220:223], v[92:95]
	v_mfma_f32_16x16x32_bf16 v[84:87], v[160:163], v[202:205], v[84:87]
	v_mfma_f32_16x16x32_bf16 v[84:87], v[166:169], v[220:223], v[84:87]
	v_mfma_f32_16x16x32_bf16 v[72:75], v[170:173], v[202:205], v[72:75]
	v_mfma_f32_16x16x32_bf16 v[72:75], v[174:177], v[220:223], v[72:75]
	s_setprio 0
	s_setprio 1
	v_mfma_f32_16x16x32_bf16 v[60:63], v[144:147], v[224:227], v[60:63]
	v_mfma_f32_16x16x32_bf16 v[60:63], v[148:151], v[228:231], v[60:63]
	v_mfma_f32_16x16x32_bf16 v[64:67], v[152:155], v[224:227], v[64:67]
	v_mfma_f32_16x16x32_bf16 v[64:67], v[156:159], v[228:231], v[64:67]
	v_mfma_f32_16x16x32_bf16 v[56:59], v[160:163], v[224:227], v[56:59]
	v_mfma_f32_16x16x32_bf16 v[56:59], v[166:169], v[228:231], v[56:59]
	v_mfma_f32_16x16x32_bf16 v[52:55], v[170:173], v[224:227], v[52:55]
	v_mfma_f32_16x16x32_bf16 v[52:55], v[174:177], v[228:231], v[52:55]
	v_mfma_f32_16x16x32_bf16 v[36:39], v[144:147], v[232:235], v[36:39]
	v_mfma_f32_16x16x32_bf16 v[36:39], v[148:151], v[236:239], v[36:39]
	v_mfma_f32_16x16x32_bf16 v[40:43], v[152:155], v[232:235], v[40:43]
	v_mfma_f32_16x16x32_bf16 v[40:43], v[156:159], v[236:239], v[40:43]
	v_mfma_f32_16x16x32_bf16 v[28:31], v[160:163], v[232:235], v[28:31]
	v_mfma_f32_16x16x32_bf16 v[28:31], v[166:169], v[236:239], v[28:31]
	v_mfma_f32_16x16x32_bf16 v[20:23], v[170:173], v[232:235], v[20:23]
	v_mfma_f32_16x16x32_bf16 v[20:23], v[174:177], v[236:239], v[20:23]
	s_setprio 0
	s_barrier
	s_add_i32 s57, 0, 0x18000
	s_add_i32 s58, 0, 0x1c000
	v_add_u32_e32 v156, s57, v1
	v_add_u32_e32 v174, s58, v1
	ds_read_b128 v[144:147], v156
	ds_read_b128 v[148:151], v156 offset:1024
	ds_read_b128 v[152:155], v156 offset:2048
	ds_read_b128 v[156:159], v156 offset:3072
	ds_read_b128 v[160:163], v174
	ds_read_b128 v[166:169], v174 offset:1024
	ds_read_b128 v[170:173], v174 offset:2048
	ds_read_b128 v[174:177], v174 offset:3072
	s_add_u32 s22, s22, s33
	s_addc_u32 s23, s23, 0
	s_mov_b32 m0, s47
	v_lshl_add_u64 v[244:245], s[22:23], 0, v[2:3]
	ds_read_b128 v[178:181], v143 offset:32768
	ds_read_b128 v[198:201], v143 offset:33792
	ds_read_b128 v[202:205], v143 offset:34816
	ds_read_b128 v[220:223], v143 offset:35840
	ds_read_b128 v[224:227], v143 offset:36864
	ds_read_b128 v[228:231], v143 offset:37888
	ds_read_b128 v[232:235], v143 offset:38912
	ds_read_b128 v[236:239], v143 offset:39936
	global_load_lds_dwordx4 v[244:245], off
	v_lshl_add_u64 v[244:245], s[22:23], 0, v[132:133]
	s_mov_b32 m0, s48
	s_nop 0
	global_load_lds_dwordx4 v[244:245], off
	s_waitcnt vmcnt(8)
	s_waitcnt lgkmcnt(0)
	s_barrier
	s_setprio 1
	s_waitcnt lgkmcnt(0)
	v_mfma_f32_16x16x32_bf16 v[100:103], v[144:147], v[178:181], v[100:103]
	v_mfma_f32_16x16x32_bf16 v[100:103], v[148:151], v[198:201], v[100:103]
	v_mfma_f32_16x16x32_bf16 v[68:71], v[152:155], v[178:181], v[68:71]
	v_mfma_f32_16x16x32_bf16 v[68:71], v[156:159], v[198:201], v[68:71]
	v_mfma_f32_16x16x32_bf16 v[16:19], v[160:163], v[178:181], v[16:19]
	v_mfma_f32_16x16x32_bf16 v[16:19], v[166:169], v[198:201], v[16:19]
	v_mfma_f32_16x16x32_bf16 v[4:7], v[170:173], v[178:181], v[4:7]
	v_mfma_f32_16x16x32_bf16 v[4:7], v[174:177], v[198:201], v[4:7]
	v_mfma_f32_16x16x32_bf16 v[116:119], v[144:147], v[202:205], v[116:119]
	v_mfma_f32_16x16x32_bf16 v[116:119], v[148:151], v[220:223], v[116:119]
	v_mfma_f32_16x16x32_bf16 v[80:83], v[152:155], v[202:205], v[80:83]
	v_mfma_f32_16x16x32_bf16 v[80:83], v[156:159], v[220:223], v[80:83]
	v_mfma_f32_16x16x32_bf16 v[32:35], v[160:163], v[202:205], v[32:35]
	v_mfma_f32_16x16x32_bf16 v[32:35], v[166:169], v[220:223], v[32:35]
	v_mfma_f32_16x16x32_bf16 v[8:11], v[170:173], v[202:205], v[8:11]
	v_mfma_f32_16x16x32_bf16 v[8:11], v[174:177], v[220:223], v[8:11]
	s_setprio 0
	s_setprio 1
	v_mfma_f32_16x16x32_bf16 v[124:127], v[144:147], v[224:227], v[124:127]
	v_mfma_f32_16x16x32_bf16 v[124:127], v[148:151], v[228:231], v[124:127]
	v_mfma_f32_16x16x32_bf16 v[104:107], v[152:155], v[224:227], v[104:107]
	v_mfma_f32_16x16x32_bf16 v[104:107], v[156:159], v[228:231], v[104:107]
	v_mfma_f32_16x16x32_bf16 v[48:51], v[160:163], v[224:227], v[48:51]
	v_mfma_f32_16x16x32_bf16 v[48:51], v[166:169], v[228:231], v[48:51]
	v_mfma_f32_16x16x32_bf16 v[12:15], v[170:173], v[224:227], v[12:15]
	v_mfma_f32_16x16x32_bf16 v[12:15], v[174:177], v[228:231], v[12:15]
	v_mfma_f32_16x16x32_bf16 v[128:131], v[144:147], v[232:235], v[128:131]
	v_mfma_f32_16x16x32_bf16 v[128:131], v[148:151], v[236:239], v[128:131]
	v_mfma_f32_16x16x32_bf16 v[120:123], v[152:155], v[232:235], v[120:123]
	v_mfma_f32_16x16x32_bf16 v[120:123], v[156:159], v[236:239], v[120:123]
	v_mfma_f32_16x16x32_bf16 v[76:79], v[160:163], v[232:235], v[76:79]
	v_mfma_f32_16x16x32_bf16 v[76:79], v[166:169], v[236:239], v[76:79]
	v_mfma_f32_16x16x32_bf16 v[24:27], v[170:173], v[232:235], v[24:27]
	v_mfma_f32_16x16x32_bf16 v[24:27], v[174:177], v[236:239], v[24:27]
	s_setprio 0
	s_barrier
; #define PG8_STAGE(bufoff, gbase, voff) do { _Pragma("unroll") for (int _i = 0; _i < 2; ++_i) \
;         __builtin_amdgcn_global_load_lds((const unsigned*)((const char*)(gbase) + (voff)[_i]), (PG8_LAS unsigned*)(lds + (bufoff) + ldsw + _i * 8192), 16, 0, 0); } while (0)
; #define PG8_LDA(dst, b, h) do { _Pragma("unroll") for (int m = 0; m < 4; ++m) _Pragma("unroll") for (int k = 0; k < 2; ++k) dst[m][k] = *(const PG8_LAS bf16x8*)(lds + PG8_SA(b, h) + aoff + m * 2048 + k * 1024); } while (0)
; #define PG8_MMA(ai, bj, At, Bt) do { __builtin_amdgcn_s_setprio(1); _Pragma("unroll") for (int m = 0; m < 4; ++m) _Pragma("unroll") for (int n = 0; n < 2; ++n) _Pragma("unroll") for (int k = 0; k < 2; ++k) \
;         acc[ai][bj][m][n] = __builtin_amdgcn_mfma_f32_16x16x32_bf16(Bt[n][k], At[m][k], acc[ai][bj][m][n], 0, 0, 0); __builtin_amdgcn_s_setprio(0); } while (0)
; #define PG8_WAIT_V(n) asm volatile("s_waitcnt vmcnt(" #n ")" ::: "memory")
; #define PG8_WAIT_L(n) asm volatile("s_waitcnt lgkmcnt(" #n ")" ::: "memory")
; #define PG8_BAR __builtin_amdgcn_s_barrier()
; #define PG8_SCHED __builtin_amdgcn_sched_barrier(0)
; template <class Epi, class Sched, bool ALIGN_EPI = false, bool SP2 = false>
; __device__ __forceinline__ void gemm_phase(PG8_LAS unsigned char* lds, const Gemm g, const Sched& S, const Epi& E) {
;     ...
;             PG8_LDA(At, 1, 1); PG8_STAGE(PG8_SB(1, 0), b3, voffB); PG8_STAGE(PG8_SB(1, 1), b3 + hstep, voffB); PG8_STAGE(PG8_SA(1, 0), a3, voffA);
;             PG8_WAIT_V(8); PG8_WAIT_L(0); PG8_BAR; PG8_MMA(1, 0, At, B0); PG8_MMA(1, 1, At, B1); PG8_BAR; PG8_SCHED;
;     ...
;         if (!has_next) break;
; #pragma unroll
;         for (int a = 0; a < 2; ++a)
; #pragma unroll
;             for (int b = 0; b < 2; ++b)
; #pragma unroll
;                 for (int m = 0; m < 4; ++m)
; #pragma unroll
;                     for (int n = 0; n < 2; ++n) acc[a][b][m][n] = (f32x4){0.f, 0.f, 0.f, 0.f};
;         cur = nxt; cA = nA; cB = nB; ++ui;
	s_add_i32 s22, s57, s13
	v_lshl_add_u64 v[184:185], v[184:185], 0, s[34:35]
	s_mov_b32 m0, s22
	ds_read_b128 v[178:181], v143 offset:49152
	ds_read_b128 v[198:201], v143 offset:50176
	ds_read_b128 v[202:205], v143 offset:51200
	ds_read_b128 v[220:223], v143 offset:52224
	ds_read_b128 v[224:227], v143 offset:53248
	ds_read_b128 v[228:231], v143 offset:54272
	ds_read_b128 v[232:235], v143 offset:55296
	ds_read_b128 v[236:239], v143 offset:56320
	global_load_lds_dwordx4 v[184:185], off
	v_lshl_add_u64 v[184:185], v[186:187], 0, s[34:35]
	s_add_i32 m0, s22, 0x2000
	s_add_i32 s22, s58, s13
	global_load_lds_dwordx4 v[184:185], off
	v_lshl_add_u64 v[184:185], v[196:197], 0, s[34:35]
	s_mov_b32 m0, s22
	s_nop 0
	global_load_lds_dwordx4 v[184:185], off
	v_lshl_add_u64 v[184:185], v[206:207], 0, s[34:35]
	s_add_i32 m0, s22, 0x2000
	s_nop 0
	global_load_lds_dwordx4 v[184:185], off
	v_lshl_add_u64 v[184:185], v[240:241], 0, s[34:35]
	s_mov_b32 m0, s50
	s_nop 0
	global_load_lds_dwordx4 v[184:185], off
	v_lshl_add_u64 v[184:185], v[242:243], 0, s[34:35]
	s_mov_b32 m0, s51
	s_nop 0
	global_load_lds_dwordx4 v[184:185], off
	s_waitcnt vmcnt(8)
	s_waitcnt lgkmcnt(0)
	s_barrier
	s_setprio 1
	s_waitcnt lgkmcnt(0)
	v_mfma_f32_16x16x32_bf16 v[108:111], v[144:147], v[178:181], v[108:111]
	v_mfma_f32_16x16x32_bf16 v[108:111], v[148:151], v[198:201], v[108:111]
	v_mfma_f32_16x16x32_bf16 v[112:115], v[152:155], v[178:181], v[112:115]
	v_mfma_f32_16x16x32_bf16 v[112:115], v[156:159], v[198:201], v[112:115]
	v_mfma_f32_16x16x32_bf16 v[96:99], v[160:163], v[178:181], v[96:99]
	v_mfma_f32_16x16x32_bf16 v[96:99], v[166:169], v[198:201], v[96:99]
	v_mfma_f32_16x16x32_bf16 v[44:47], v[170:173], v[178:181], v[44:47]
	v_mfma_f32_16x16x32_bf16 v[44:47], v[174:177], v[198:201], v[44:47]
	v_mfma_f32_16x16x32_bf16 v[88:91], v[144:147], v[202:205], v[88:91]
	v_mfma_f32_16x16x32_bf16 v[88:91], v[148:151], v[220:223], v[88:91]
	v_mfma_f32_16x16x32_bf16 v[92:95], v[152:155], v[202:205], v[92:95]
	v_mfma_f32_16x16x32_bf16 v[92:95], v[156:159], v[220:223], v[92:95]
	v_mfma_f32_16x16x32_bf16 v[84:87], v[160:163], v[202:205], v[84:87]
	v_mfma_f32_16x16x32_bf16 v[84:87], v[166:169], v[220:223], v[84:87]
	v_mfma_f32_16x16x32_bf16 v[72:75], v[170:173], v[202:205], v[72:75]
	v_mfma_f32_16x16x32_bf16 v[72:75], v[174:177], v[220:223], v[72:75]
	s_setprio 0
	s_setprio 1
	v_mfma_f32_16x16x32_bf16 v[60:63], v[144:147], v[224:227], v[60:63]
	v_mfma_f32_16x16x32_bf16 v[60:63], v[148:151], v[228:231], v[60:63]
	v_mfma_f32_16x16x32_bf16 v[64:67], v[152:155], v[224:227], v[64:67]
	v_mfma_f32_16x16x32_bf16 v[64:67], v[156:159], v[228:231], v[64:67]
	v_mfma_f32_16x16x32_bf16 v[56:59], v[160:163], v[224:227], v[56:59]
	v_mfma_f32_16x16x32_bf16 v[56:59], v[166:169], v[228:231], v[56:59]
	v_mfma_f32_16x16x32_bf16 v[52:55], v[170:173], v[224:227], v[52:55]
	v_mfma_f32_16x16x32_bf16 v[52:55], v[174:177], v[228:231], v[52:55]
	v_mfma_f32_16x16x32_bf16 v[36:39], v[144:147], v[232:235], v[36:39]
	v_mfma_f32_16x16x32_bf16 v[36:39], v[148:151], v[236:239], v[36:39]
	v_mfma_f32_16x16x32_bf16 v[40:43], v[152:155], v[232:235], v[40:43]
	v_mfma_f32_16x16x32_bf16 v[40:43], v[156:159], v[236:239], v[40:43]
	v_mfma_f32_16x16x32_bf16 v[28:31], v[160:163], v[232:235], v[28:31]
	v_mfma_f32_16x16x32_bf16 v[28:31], v[166:169], v[236:239], v[28:31]
	v_mfma_f32_16x16x32_bf16 v[20:23], v[170:173], v[232:235], v[20:23]
	v_mfma_f32_16x16x32_bf16 v[20:23], v[174:177], v[236:239], v[20:23]
	s_setprio 0
	s_barrier
	s_add_u32 s20, s20, 0x100
	s_addc_u32 s21, s21, 0
	v_lshl_add_u64 v[140:141], v[140:141], 0, s[62:63]
	v_lshl_add_u64 v[138:139], v[138:139], 0, s[62:63]
	s_cmp_ge_u32 s56, s29
	s_mov_b32 s22, s56
	s_cbranch_scc0 .LBB11_1896
	s_and_b64 vcc, exec, s[38:39]
	s_cbranch_vccnz .LBB11_1884
	v_mov_b32_e32 v20, 0
	s_mov_b32 s42, s53
	s_mov_b32 s28, s54
	s_mov_b64 s[14:15], s[18:19]
	s_mov_b64 s[16:17], s[4:5]
	s_mov_b32 s52, s55
	v_mov_b32_e32 v21, v20
	v_mov_b32_e32 v22, v20
	v_mov_b32_e32 v23, v20
	v_mov_b32_e32 v28, v20
	v_mov_b32_e32 v29, v20
	v_mov_b32_e32 v30, v20
	v_mov_b32_e32 v31, v20
	v_mov_b32_e32 v52, v20
	v_mov_b32_e32 v53, v20
	v_mov_b32_e32 v54, v20
	v_mov_b32_e32 v55, v20
	v_mov_b32_e32 v56, v20
	v_mov_b32_e32 v57, v20
	v_mov_b32_e32 v58, v20
	v_mov_b32_e32 v59, v20
	v_mov_b32_e32 v72, v20
	v_mov_b32_e32 v73, v20
	v_mov_b32_e32 v74, v20
	v_mov_b32_e32 v75, v20
	v_mov_b32_e32 v84, v20
	v_mov_b32_e32 v85, v20
	v_mov_b32_e32 v86, v20
	v_mov_b32_e32 v87, v20
	v_mov_b32_e32 v44, v20
	v_mov_b32_e32 v45, v20
	v_mov_b32_e32 v46, v20
	v_mov_b32_e32 v47, v20
	v_mov_b32_e32 v96, v20
	v_mov_b32_e32 v97, v20
	v_mov_b32_e32 v98, v20
	v_mov_b32_e32 v99, v20
	v_mov_b32_e32 v40, v20
	v_mov_b32_e32 v41, v20
	v_mov_b32_e32 v42, v20
	v_mov_b32_e32 v43, v20
	v_mov_b32_e32 v36, v20
	v_mov_b32_e32 v37, v20
	v_mov_b32_e32 v38, v20
	v_mov_b32_e32 v39, v20
	v_mov_b32_e32 v64, v20
	v_mov_b32_e32 v65, v20
	v_mov_b32_e32 v66, v20
	v_mov_b32_e32 v67, v20
	v_mov_b32_e32 v60, v20
	v_mov_b32_e32 v61, v20
	v_mov_b32_e32 v62, v20
	v_mov_b32_e32 v63, v20
	v_mov_b32_e32 v92, v20
	v_mov_b32_e32 v93, v20
	v_mov_b32_e32 v94, v20
	v_mov_b32_e32 v95, v20
	v_mov_b32_e32 v88, v20
	v_mov_b32_e32 v89, v20
	v_mov_b32_e32 v90, v20
	v_mov_b32_e32 v91, v20
	v_mov_b32_e32 v112, v20
	v_mov_b32_e32 v113, v20
	v_mov_b32_e32 v114, v20
	v_mov_b32_e32 v115, v20
	v_mov_b32_e32 v108, v20
	v_mov_b32_e32 v109, v20
	v_mov_b32_e32 v110, v20
	v_mov_b32_e32 v111, v20
	v_mov_b32_e32 v24, v20
	v_mov_b32_e32 v25, v20
	v_mov_b32_e32 v26, v20
	v_mov_b32_e32 v27, v20
	v_mov_b32_e32 v76, v20
	v_mov_b32_e32 v77, v20
	v_mov_b32_e32 v78, v20
	v_mov_b32_e32 v79, v20
	v_mov_b32_e32 v12, v20
	v_mov_b32_e32 v13, v20
	v_mov_b32_e32 v14, v20
	v_mov_b32_e32 v15, v20
	v_mov_b32_e32 v48, v20
	v_mov_b32_e32 v49, v20
	v_mov_b32_e32 v50, v20
	v_mov_b32_e32 v51, v20
	v_mov_b32_e32 v8, v20
	v_mov_b32_e32 v9, v20
	v_mov_b32_e32 v10, v20
	v_mov_b32_e32 v11, v20
	v_mov_b32_e32 v32, v20
	v_mov_b32_e32 v33, v20
	v_mov_b32_e32 v34, v20
	v_mov_b32_e32 v35, v20
	v_mov_b32_e32 v4, v20
	v_mov_b32_e32 v5, v20
	v_mov_b32_e32 v6, v20
	v_mov_b32_e32 v7, v20
	v_mov_b32_e32 v16, v20
	v_mov_b32_e32 v17, v20
	v_mov_b32_e32 v18, v20
	v_mov_b32_e32 v19, v20
	v_mov_b32_e32 v120, v20
	v_mov_b32_e32 v121, v20
	v_mov_b32_e32 v122, v20
	v_mov_b32_e32 v123, v20
	v_mov_b32_e32 v128, v20
	v_mov_b32_e32 v129, v20
	v_mov_b32_e32 v130, v20
	v_mov_b32_e32 v131, v20
	v_mov_b32_e32 v104, v20
	v_mov_b32_e32 v105, v20
	v_mov_b32_e32 v106, v20
	v_mov_b32_e32 v107, v20
	v_mov_b32_e32 v124, v20
	v_mov_b32_e32 v125, v20
	v_mov_b32_e32 v126, v20
	v_mov_b32_e32 v127, v20
	v_mov_b32_e32 v80, v20
	v_mov_b32_e32 v81, v20
	v_mov_b32_e32 v82, v20
	v_mov_b32_e32 v83, v20
	v_mov_b32_e32 v116, v20
	v_mov_b32_e32 v117, v20
	v_mov_b32_e32 v118, v20
	v_mov_b32_e32 v119, v20
	v_mov_b32_e32 v68, v20
	v_mov_b32_e32 v69, v20
	v_mov_b32_e32 v70, v20
	v_mov_b32_e32 v71, v20
	v_mov_b32_e32 v100, v20
	v_mov_b32_e32 v101, v20
	v_mov_b32_e32 v102, v20
	v_mov_b32_e32 v103, v20
	s_branch .LBB11_1884
